# 64 workgroups (8 per XCD) run the weight-conversion class first with all 64 row loads of an item in flight, then the attention classes
# baseline (speedup 1.0000x reference)
; #define LAS __attribute__((address_space(3)))
; __device__ __forceinline__ unsigned xb_xcc_id() { return (unsigned)__builtin_amdgcn_s_getreg((3 << 11) | 20) & 0xFu; }
; __device__ __forceinline__ float wave_sum(float v) { v += lx<1>(v); v += lx<2>(v); v += lx<4>(v); v += lx<8>(v); v += lx<16>(v); return half_sum(v); }
; #define ARG_IN(i) ((const float*)karg64(8 * (i)))
; #define ARG_WS() ((unsigned char*)karg64(8 * 19))
; #define WG_DRAW(cls, q) LAS int* slot = (LAS int*)(lds + MISC_OFF + 64); \
;         if (threadIdx.x == 0) *slot = (int)__hip_atomic_fetch_add(XQ_HEAD(cls, q), 1u, RLX_AGENT); \
;         __syncthreads(); const int it = *slot; __syncthreads();
; template <int ATTM> __device__ __forceinline__ void attention_phase(int layer, int lane, int rep, LAS unsigned char* lds, int wave) {
;     asm volatile("" : "+s"(wave));
;     ...
;     if ((ATTM & 2) && PK(2)) {
; #pragma unroll 1
;         for (int qq = 0; qq < 8; ++qq) { const int q = ((int)(xb_xcc_id() & 7u) + qq) & 7;
;             for (;;) { WG_DRAW(0, q); if (it >= 32) break;
;                 unsigned char* ws = ARG_WS(); int tid = threadIdx.x; asm volatile("" : "+v"(tid));
;                 const float* lamv = ARG_IN(A_LAM) + (size_t)layer * 4 * 64;
;                 const float lam_init = 0.8f - 0.6f * __builtin_amdgcn_exp2f(-0.3f * 1.4426950408889634f * (float)layer);
;                 const float sa = wave_sum(lamv[lane] * lamv[64 + lane]), sb = wave_sum(lamv[128 + lane] * lamv[192 + lane]);
;                 const float lam = __builtin_amdgcn_exp2f(1.4426950408889634f * sa) - __builtin_amdgcn_exp2f(1.4426950408889634f * sb) + lam_init;
;                 dif_coop(WSP(bf16, WS_PROJ), ws + WS_VTB, WSP(bf16, WS_O), lam, ARG_IN(A_SUBG) + (size_t)layer * 128, 1.f - lam_init, q, 31 - it, lds, tid); } } }
.Lmy_att_preamble:
	v_readlane_b32 s6, v255, 21
	s_load_dword s4, s[72:73], 0x0
	v_mov_b32_e32 v4, v0
	v_cvt_f32_u32_e32 v1, s6
	v_mov_b32_e32 v2, 0x3f4ccccd
	s_waitcnt lgkmcnt(0)
	v_mul_f32_e32 v1, 0xbedd9914, v1
	v_exp_f32_e32 v1, v1
	v_readlane_b32 s7, v255, 22
	v_readfirstlane_b32 s4, v4
	s_mul_i32 s33, s6, 40
	v_fmamk_f32 v1, v1, 0xbf19999a, v2
	v_and_b32_e32 v2, 63, v4
	s_lshl_b64 s[2:3], s[6:7], 10
	s_lshl_b64 s[72:73], s[6:7], 9
	s_waitcnt vmcnt(0)
	v_sub_f32_e32 v182, 1.0, v1
	s_ashr_i32 s94, s4, 6
	s_mov_b32 s6, 0
	s_mov_b32 s101, 0
	v_lshlrev_b32_e32 v172, 2, v2
	s_cmp_lg_u32 s99, 0
	s_cbranch_scc1 .LBB0_549
	s_lshr_b32 s4, s66, 3
	s_and_b32 s4, s4, 3
	s_cmp_eq_u32 s4, 0
	s_cbranch_scc0 .LBB0_549
	s_mov_b32 s99, 1
	v_writelane_b32 v255, s33, 25
	v_writelane_b32 v255, s94, 27
	s_nop 1
	s_branch .LBB0_749
	s_branch .LBB0_549

; __device__ __forceinline__ unsigned xb_xcc_id() { return (unsigned)__builtin_amdgcn_s_getreg((3 << 11) | 20) & 0xFu; }
; #define ARG_WS() ((unsigned char*)karg64(8 * 19))
; #define WV_DRAW(cls, q, n) int it = 0; if (__builtin_amdgcn_mbcnt_hi(~0u, __builtin_amdgcn_mbcnt_lo(~0u, 0u)) == 0u) it = (int)__hip_atomic_fetch_add(XQ_HEAD(cls, q), (unsigned)(n), RLX_AGENT); it = __builtin_amdgcn_readfirstlane(it);
; template <int ATTM> __device__ __forceinline__ void attention_phase(int layer, int lane, int rep, LAS unsigned char* lds, int wave) {
;     ...
;     if ((ATTM & 8) && PK(8)) {
; #pragma unroll 1
;         for (int qq = 0; qq < 8; ++qq) { const int q = ((int)(xb_xcc_id() & 7u) + qq) & 7;
;             for (;;) { WV_DRAW(3, q, 1); if (it >= 96) break; unsigned char* ws = ARG_WS();
;                 const int chunk = 3 * q + it / 32, idx = (chunk & 3) * 32 + (it & 31);
;                 dil_item_mfma(WSP(bf16, WS_PROJ), ws + WS_VTB, WSP(bf16, WS_O), lds + wave * 16384, chunk >> 2, idx & 15, idx >> 4, lane); } } }
.LBB0_749:
	v_readlane_b32 s2, v255, 27
	s_lshl_b32 s2, s2, 14
	v_readlane_b32 s64, v255, 25
	s_add_i32 s46, s2, 0
	v_readlane_b32 s72, v255, 16
	v_readlane_b32 s78, v255, 18
	s_add_i32 s6, s64, 24
	s_mov_b32 s7, 0
	s_mov_b32 s101, 0
	v_cmp_eq_u32_e64 s[38:39], 0, v239
	s_add_i32 s8, s46, 0x800
	s_add_i32 s9, s46, 0x2400
	s_add_i32 s10, s46, 0x2800
	s_add_i32 s11, s46, 0x2c00
	s_add_i32 s42, s46, 0x1400
	s_add_i32 s43, s46, 0x3400
	s_add_i32 s44, s46, 0x3800
	s_add_i32 s45, s46, 0x3c00
	v_readlane_b32 s66, v254, 0
	v_readlane_b32 s67, v254, 1
	v_readlane_b32 s68, v254, 2
	v_readlane_b32 s73, v255, 17
	v_readlane_b32 s79, v255, 19
	s_cmp_eq_u32 s99, 1
	s_cbranch_scc1 .LBB0_876
	s_branch .LBB0_751

; #define LAS __attribute__((address_space(3)))
; __device__ __forceinline__ void tr64_item(const float* W, int K, int N, int srccol, bf16* WT, int destrow0  , int k0, LAS unsigned char* scr, int lane) {
;     const float* src = W + (size_t)k0 * N + (srccol >= 0 ? srccol : 0);
; #pragma unroll
;     for (int h = 0; h < 2; ++h) { float v[32];
; #pragma unroll
;         for (int i = 0; i < 32; ++i) v[i] = srccol >= 0 ? src[(size_t)(32 * h + i) * N] : 0.f;
; __device__ __forceinline__ void conv_item(const float* w_in, const float* w_out, const float* w_gate, const float* w_up, const float* w_down, unsigned char* ws, int layer, int r, LAS unsigned char* scr, int lane) {
;     ...
;         { const int nblk = DM / 64, kb = r / nblk, nb = r % nblk;
;             tr64_item(w_down + (size_t)layer * DFF * DM, DFF, DM, nb * 64 + lane, (bf16*)(wl + W_D), nb * 64, kb * 64, scr, lane); }
.LBB0_891:
	s_waitcnt lgkmcnt(0)
	s_load_dwordx2 s[2:3], s[0:1], 0x30
	s_load_dwordx2 s[14:15], s[0:1], 0x68
	s_load_dwordx2 s[16:17], s[0:1], 0x70
	s_load_dwordx2 s[22:23], s[0:1], 0x78
	s_load_dwordx2 s[20:21], s[0:1], 0x80
	s_add_i32 s6, s51, s54
	v_mov_b32_e32 v1, v239
	s_cmpk_gt_i32 s6, 0xbff
	s_mov_b64 s[24:25], -1
	s_cbranch_scc0 .LBB0_1284
	s_cmpk_gt_u32 s6, 0xfff
	s_cbranch_scc0 .LBB0_1153
	s_cmpk_gt_u32 s6, 0x25ff
	s_cbranch_scc0 .LBB0_1023
	s_waitcnt lgkmcnt(0)
	s_add_u32 s7, s20, s37
	s_addc_u32 s10, s21, s36
	s_and_b32 s8, s65, 0x7fffffc0
	s_and_b32 s4, s64, 0x7c0
	s_add_i32 s18, s8, 0xffffb400
	v_add_u32_e32 v2, s4, v1
	s_lshl_b64 s[8:9], s[18:19], 13
	s_add_u32 s8, s7, s8
	v_cmp_lt_i32_e64 s[40:41], -1, v2
	s_addc_u32 s9, s10, s9
	v_mov_b32_e32 v7, 0
	v_cndmask_b32_e64 v2, 0, v2, s[40:41]
	v_lshl_add_u64 v[4:5], v[2:3], 2, s[8:9]
	v_mov_b32_e32 v2, 0
	s_cmp_eq_u64 s[40:41], exec
	s_cbranch_scc1 .Lmy_cv0_nz
	v_mov_b32_e32 v146, 0
	v_mov_b32_e32 v147, 0
	v_mov_b32_e32 v148, 0
	v_mov_b32_e32 v149, 0
	v_mov_b32_e32 v150, 0
	v_mov_b32_e32 v151, 0
	v_mov_b32_e32 v152, 0
	v_mov_b32_e32 v153, 0
	v_mov_b32_e32 v154, 0
	v_mov_b32_e32 v155, 0
	v_mov_b32_e32 v156, 0
	v_mov_b32_e32 v157, 0
	v_mov_b32_e32 v158, 0
	v_mov_b32_e32 v159, 0
	v_mov_b32_e32 v160, 0
	v_mov_b32_e32 v161, 0
	v_mov_b32_e32 v162, 0
	v_mov_b32_e32 v163, 0
	v_mov_b32_e32 v164, 0
	v_mov_b32_e32 v165, 0
	v_mov_b32_e32 v166, 0
	v_mov_b32_e32 v167, 0
	v_mov_b32_e32 v168, 0
	v_mov_b32_e32 v169, 0
	v_mov_b32_e32 v170, 0
	v_mov_b32_e32 v171, 0
	v_mov_b32_e32 v172, 0
	v_mov_b32_e32 v173, 0
	v_mov_b32_e32 v174, 0
	v_mov_b32_e32 v175, 0
	v_mov_b32_e32 v176, 0
	v_mov_b32_e32 v177, 0
	v_mov_b32_e32 v8, 0
	v_mov_b32_e32 v7, 0
	v_mov_b32_e32 v10, 0
	v_mov_b32_e32 v9, 0
	v_mov_b32_e32 v12, 0
	v_mov_b32_e32 v11, 0
	v_mov_b32_e32 v14, 0
	v_mov_b32_e32 v13, 0
	v_mov_b32_e32 v16, 0
	v_mov_b32_e32 v15, 0
	v_mov_b32_e32 v18, 0
	v_mov_b32_e32 v17, 0
	v_mov_b32_e32 v20, 0
	v_mov_b32_e32 v19, 0
	v_mov_b32_e32 v22, 0
	v_mov_b32_e32 v21, 0
	v_mov_b32_e32 v24, 0
	v_mov_b32_e32 v23, 0
	v_mov_b32_e32 v26, 0
	v_mov_b32_e32 v25, 0
	v_mov_b32_e32 v28, 0
	v_mov_b32_e32 v27, 0
	v_mov_b32_e32 v30, 0
	v_mov_b32_e32 v29, 0
	v_mov_b32_e32 v32, 0
	v_mov_b32_e32 v31, 0
	v_mov_b32_e32 v34, 0
	v_mov_b32_e32 v33, 0
	v_mov_b32_e32 v36, 0
	v_mov_b32_e32 v35, 0
	v_mov_b32_e32 v38, 0
	v_mov_b32_e32 v37, 0
.Lmy_cv0_nz:
	v_mov_b64_e32 v[178:179], v[4:5]
	v_mov_b32_e32 v214, 0x2000
	v_mov_b32_e32 v215, 0
	s_and_saveexec_b64 s[20:21], s[40:41]
	global_load_dword v146, v[178:179], off
	v_lshl_add_u64 v[178:179], v[178:179], 0, v[214:215]
	global_load_dword v147, v[178:179], off
	v_lshl_add_u64 v[178:179], v[178:179], 0, v[214:215]
	global_load_dword v148, v[178:179], off
	v_lshl_add_u64 v[178:179], v[178:179], 0, v[214:215]
	global_load_dword v149, v[178:179], off
	v_lshl_add_u64 v[178:179], v[178:179], 0, v[214:215]
	global_load_dword v150, v[178:179], off
	v_lshl_add_u64 v[178:179], v[178:179], 0, v[214:215]
	global_load_dword v151, v[178:179], off
	v_lshl_add_u64 v[178:179], v[178:179], 0, v[214:215]
	global_load_dword v152, v[178:179], off
	v_lshl_add_u64 v[178:179], v[178:179], 0, v[214:215]
	global_load_dword v153, v[178:179], off
	v_lshl_add_u64 v[178:179], v[178:179], 0, v[214:215]
	global_load_dword v154, v[178:179], off
	v_lshl_add_u64 v[178:179], v[178:179], 0, v[214:215]
	global_load_dword v155, v[178:179], off
	v_lshl_add_u64 v[178:179], v[178:179], 0, v[214:215]
	global_load_dword v156, v[178:179], off
	v_lshl_add_u64 v[178:179], v[178:179], 0, v[214:215]
	global_load_dword v157, v[178:179], off
	v_lshl_add_u64 v[178:179], v[178:179], 0, v[214:215]
	global_load_dword v158, v[178:179], off
	v_lshl_add_u64 v[178:179], v[178:179], 0, v[214:215]
	global_load_dword v159, v[178:179], off
	v_lshl_add_u64 v[178:179], v[178:179], 0, v[214:215]
	global_load_dword v160, v[178:179], off
	v_lshl_add_u64 v[178:179], v[178:179], 0, v[214:215]
	global_load_dword v161, v[178:179], off
	v_lshl_add_u64 v[178:179], v[178:179], 0, v[214:215]
	global_load_dword v162, v[178:179], off
	v_lshl_add_u64 v[178:179], v[178:179], 0, v[214:215]
	global_load_dword v163, v[178:179], off
	v_lshl_add_u64 v[178:179], v[178:179], 0, v[214:215]
	global_load_dword v164, v[178:179], off
	v_lshl_add_u64 v[178:179], v[178:179], 0, v[214:215]
	global_load_dword v165, v[178:179], off
	v_lshl_add_u64 v[178:179], v[178:179], 0, v[214:215]
	global_load_dword v166, v[178:179], off
	v_lshl_add_u64 v[178:179], v[178:179], 0, v[214:215]
	global_load_dword v167, v[178:179], off
	v_lshl_add_u64 v[178:179], v[178:179], 0, v[214:215]
	global_load_dword v168, v[178:179], off
	v_lshl_add_u64 v[178:179], v[178:179], 0, v[214:215]
	global_load_dword v169, v[178:179], off
	v_lshl_add_u64 v[178:179], v[178:179], 0, v[214:215]
	global_load_dword v170, v[178:179], off
	v_lshl_add_u64 v[178:179], v[178:179], 0, v[214:215]
	global_load_dword v171, v[178:179], off
	v_lshl_add_u64 v[178:179], v[178:179], 0, v[214:215]
	global_load_dword v172, v[178:179], off
	v_lshl_add_u64 v[178:179], v[178:179], 0, v[214:215]
	global_load_dword v173, v[178:179], off
	v_lshl_add_u64 v[178:179], v[178:179], 0, v[214:215]
	global_load_dword v174, v[178:179], off
	v_lshl_add_u64 v[178:179], v[178:179], 0, v[214:215]
	global_load_dword v175, v[178:179], off
	v_lshl_add_u64 v[178:179], v[178:179], 0, v[214:215]
	global_load_dword v176, v[178:179], off
	v_lshl_add_u64 v[178:179], v[178:179], 0, v[214:215]
	global_load_dword v177, v[178:179], off
	v_lshl_add_u64 v[178:179], v[178:179], 0, v[214:215]
	global_load_dword v8, v[178:179], off
	v_lshl_add_u64 v[178:179], v[178:179], 0, v[214:215]
; #define LAS __attribute__((address_space(3)))
; #define LDS_WAIT() asm volatile("s_waitcnt lgkmcnt(0)" ::: "memory")
; __device__ __forceinline__ unsigned pk2(float lo, float hi) { pk2_f2_t v = {lo, hi}; pk2_b2_t b = __builtin_convertvector(v, pk2_b2_t); return __builtin_bit_cast(unsigned, b); }
; __device__ __forceinline__ void tr64_item(const float* W, int K, int N, int srccol, bf16* WT, int destrow0  , int k0, LAS unsigned char* scr, int lane) {
;     ...
;     for (int h = 0; h < 2; ++h) { float v[32];
; #pragma unroll
;         for (int i = 0; i < 32; ++i) v[i] = srccol >= 0 ? src[(size_t)(32 * h + i) * N] : 0.f;
; #pragma unroll
;         for (int c = 0; c < 4; ++c) { v4u o; o.x = pk2(v[8 * c], v[8 * c + 1]); o.y = pk2(v[8 * c + 2], v[8 * c + 3]); o.z = pk2(v[8 * c + 4], v[8 * c + 5]); o.w = pk2(v[8 * c + 6], v[8 * c + 7]);
;             *(LAS v4u*)(scr + lane * 128 + (((4 * h + c) ^ (lane & 7)) << 4)) = o; } }
;     LDS_WAIT(); asm volatile("" ::: "memory");
;     const int r = lane >> 3, c = lane & 7;
; #pragma unroll
;     for (int j = 0; j < 8; ++j) { const int n = r + 8 * j; const v4u o = *(const LAS v4u*)(scr + n * 128 + ((c ^ (n & 7)) << 4));
;         *(v4u*)(WT + (size_t)(destrow0 + n) * K + k0 + 8 * c) = o; }
	global_load_dword v7, v[178:179], off
	v_lshl_add_u64 v[178:179], v[178:179], 0, v[214:215]
	global_load_dword v10, v[178:179], off
	v_lshl_add_u64 v[178:179], v[178:179], 0, v[214:215]
	global_load_dword v9, v[178:179], off
	v_lshl_add_u64 v[178:179], v[178:179], 0, v[214:215]
	global_load_dword v12, v[178:179], off
	v_lshl_add_u64 v[178:179], v[178:179], 0, v[214:215]
	global_load_dword v11, v[178:179], off
	v_lshl_add_u64 v[178:179], v[178:179], 0, v[214:215]
	global_load_dword v14, v[178:179], off
	v_lshl_add_u64 v[178:179], v[178:179], 0, v[214:215]
	global_load_dword v13, v[178:179], off
	v_lshl_add_u64 v[178:179], v[178:179], 0, v[214:215]
	global_load_dword v16, v[178:179], off
	v_lshl_add_u64 v[178:179], v[178:179], 0, v[214:215]
	global_load_dword v15, v[178:179], off
	v_lshl_add_u64 v[178:179], v[178:179], 0, v[214:215]
	global_load_dword v18, v[178:179], off
	v_lshl_add_u64 v[178:179], v[178:179], 0, v[214:215]
	global_load_dword v17, v[178:179], off
	v_lshl_add_u64 v[178:179], v[178:179], 0, v[214:215]
	global_load_dword v20, v[178:179], off
	v_lshl_add_u64 v[178:179], v[178:179], 0, v[214:215]
	global_load_dword v19, v[178:179], off
	v_lshl_add_u64 v[178:179], v[178:179], 0, v[214:215]
	global_load_dword v22, v[178:179], off
	v_lshl_add_u64 v[178:179], v[178:179], 0, v[214:215]
	global_load_dword v21, v[178:179], off
	v_lshl_add_u64 v[178:179], v[178:179], 0, v[214:215]
	global_load_dword v24, v[178:179], off
	v_lshl_add_u64 v[178:179], v[178:179], 0, v[214:215]
	global_load_dword v23, v[178:179], off
	v_lshl_add_u64 v[178:179], v[178:179], 0, v[214:215]
	global_load_dword v26, v[178:179], off
	v_lshl_add_u64 v[178:179], v[178:179], 0, v[214:215]
	global_load_dword v25, v[178:179], off
	v_lshl_add_u64 v[178:179], v[178:179], 0, v[214:215]
	global_load_dword v28, v[178:179], off
	v_lshl_add_u64 v[178:179], v[178:179], 0, v[214:215]
	global_load_dword v27, v[178:179], off
	v_lshl_add_u64 v[178:179], v[178:179], 0, v[214:215]
	global_load_dword v30, v[178:179], off
	v_lshl_add_u64 v[178:179], v[178:179], 0, v[214:215]
	global_load_dword v29, v[178:179], off
	v_lshl_add_u64 v[178:179], v[178:179], 0, v[214:215]
	global_load_dword v32, v[178:179], off
	v_lshl_add_u64 v[178:179], v[178:179], 0, v[214:215]
	global_load_dword v31, v[178:179], off
	v_lshl_add_u64 v[178:179], v[178:179], 0, v[214:215]
	global_load_dword v34, v[178:179], off
	v_lshl_add_u64 v[178:179], v[178:179], 0, v[214:215]
	global_load_dword v33, v[178:179], off
	v_lshl_add_u64 v[178:179], v[178:179], 0, v[214:215]
	global_load_dword v36, v[178:179], off
	v_lshl_add_u64 v[178:179], v[178:179], 0, v[214:215]
	global_load_dword v35, v[178:179], off
	v_lshl_add_u64 v[178:179], v[178:179], 0, v[214:215]
	global_load_dword v38, v[178:179], off
	v_lshl_add_u64 v[178:179], v[178:179], 0, v[214:215]
	global_load_dword v37, v[178:179], off
	s_or_b64 exec, exec, s[20:21]
	s_waitcnt vmcnt(32)
	v_lshlrev_b32_e32 v2, 4, v1
	v_lshl_add_u32 v6, v1, 7, s46
	v_and_b32_e32 v2, 0x70, v2
	v_cvt_pk_bf16_f32 v180, v146, v147
	v_cvt_pk_bf16_f32 v181, v148, v149
	v_cvt_pk_bf16_f32 v182, v150, v151
	v_cvt_pk_bf16_f32 v183, v152, v153
	v_add_u32_e32 v184, v6, v2
	ds_write_b128 v184, v[180:183]
	v_cvt_pk_bf16_f32 v180, v154, v155
	v_cvt_pk_bf16_f32 v181, v156, v157
	v_cvt_pk_bf16_f32 v182, v158, v159
	v_cvt_pk_bf16_f32 v183, v160, v161
	v_xad_u32 v184, v2, 16, v6
	ds_write_b128 v184, v[180:183]
	v_cvt_pk_bf16_f32 v180, v162, v163
	v_cvt_pk_bf16_f32 v181, v164, v165
	v_cvt_pk_bf16_f32 v182, v166, v167
	v_cvt_pk_bf16_f32 v183, v168, v169
	v_xad_u32 v184, v2, 32, v6
	ds_write_b128 v184, v[180:183]
	v_cvt_pk_bf16_f32 v180, v170, v171
	v_cvt_pk_bf16_f32 v181, v172, v173
	v_cvt_pk_bf16_f32 v182, v174, v175
	v_cvt_pk_bf16_f32 v183, v176, v177
	v_xad_u32 v184, v2, 48, v6
	ds_write_b128 v184, v[180:183]
	s_waitcnt vmcnt(0)
	s_waitcnt vmcnt(0) lgkmcnt(0)
	v_cvt_pk_bf16_f32 v8, v8, v7
	v_cvt_pk_bf16_f32 v9, v10, v9
	v_cvt_pk_bf16_f32 v10, v12, v11
	v_cvt_pk_bf16_f32 v11, v14, v13
	v_xad_u32 v4, v2, 64, v6
	ds_write_b128 v4, v[8:11]
	v_cvt_pk_bf16_f32 v8, v16, v15
	v_cvt_pk_bf16_f32 v9, v18, v17
	v_cvt_pk_bf16_f32 v10, v20, v19
	v_cvt_pk_bf16_f32 v11, v22, v21
	v_xad_u32 v4, v2, s92, v6
	ds_write_b128 v4, v[8:11]
	v_cvt_pk_bf16_f32 v8, v24, v23
	v_cvt_pk_bf16_f32 v9, v26, v25
	v_cvt_pk_bf16_f32 v10, v28, v27
	v_cvt_pk_bf16_f32 v11, v30, v29
	v_xad_u32 v4, v2, s81, v6
	ds_write_b128 v4, v[8:11]
	v_cvt_pk_bf16_f32 v8, v32, v31
	v_cvt_pk_bf16_f32 v9, v34, v33
	v_cvt_pk_bf16_f32 v10, v36, v35
	v_cvt_pk_bf16_f32 v11, v38, v37
	v_xad_u32 v4, v2, s85, v6
	v_ashrrev_i32_e32 v12, 3, v1
	ds_write_b128 v4, v[8:11]
	v_xor_b32_e32 v4, v12, v1
	v_lshlrev_b32_e32 v4, 4, v4
	v_and_b32_e32 v4, 0x70, v4
	s_waitcnt lgkmcnt(0)
	v_add_u32_e32 v13, s46, v4
	v_lshl_add_u32 v4, v12, 7, v13
	s_lshl_b64 s[8:9], s[18:19], 1
	ds_read_b128 v[4:7], v4
	s_add_u32 s8, s58, s8
	s_addc_u32 s9, s59, s9
	v_lshl_add_u64 v[8:9], s[8:9], 0, v[2:3]
	v_add_u32_e32 v2, s4, v12
	v_mad_i64_i32 v[10:11], s[8:9], v2, s89, v[8:9]
	v_add_u32_e32 v2, 8, v12
	s_waitcnt lgkmcnt(0)
	flat_store_dwordx4 v[10:11], v[4:7]
	s_mov_b64 s[24:25], 0
	s_nop 0
	v_lshl_add_u32 v4, v2, 7, v13
	ds_read_b128 v[4:7], v4
	v_add_u32_e32 v2, s4, v2
	v_mad_i64_i32 v[10:11], s[8:9], v2, s89, v[8:9]
	v_add_u32_e32 v2, 16, v12
	s_waitcnt lgkmcnt(0)
	flat_store_dwordx4 v[10:11], v[4:7]
	s_nop 1
	v_lshl_add_u32 v4, v2, 7, v13
	ds_read_b128 v[4:7], v4
	v_add_u32_e32 v2, s4, v2
	v_mad_i64_i32 v[10:11], s[8:9], v2, s89, v[8:9]
	v_add_u32_e32 v2, 24, v12
	s_waitcnt lgkmcnt(0)
	flat_store_dwordx4 v[10:11], v[4:7]
	s_nop 1
	v_lshl_add_u32 v4, v2, 7, v13
	ds_read_b128 v[4:7], v4
	v_add_u32_e32 v2, s4, v2
	v_mad_i64_i32 v[10:11], s[8:9], v2, s89, v[8:9]
	v_add_u32_e32 v2, 32, v12
	s_waitcnt lgkmcnt(0)
	flat_store_dwordx4 v[10:11], v[4:7]
	s_nop 1
	v_lshl_add_u32 v4, v2, 7, v13
	ds_read_b128 v[4:7], v4
	v_add_u32_e32 v2, s4, v2
	v_mad_i64_i32 v[10:11], s[8:9], v2, s89, v[8:9]
	v_add_u32_e32 v2, 40, v12
	s_waitcnt lgkmcnt(0)
	flat_store_dwordx4 v[10:11], v[4:7]
	s_nop 1
	v_lshl_add_u32 v4, v2, 7, v13
	ds_read_b128 v[4:7], v4
	v_add_u32_e32 v2, s4, v2
	v_mad_i64_i32 v[10:11], s[8:9], v2, s89, v[8:9]
	v_add_u32_e32 v2, 48, v12
	s_waitcnt lgkmcnt(0)
	flat_store_dwordx4 v[10:11], v[4:7]
	s_nop 1
	v_lshl_add_u32 v4, v2, 7, v13
	ds_read_b128 v[4:7], v4
	v_add_u32_e32 v2, s4, v2
	v_mad_i64_i32 v[10:11], s[8:9], v2, s89, v[8:9]
	v_add_u32_e32 v2, 56, v12
	s_waitcnt lgkmcnt(0)
	flat_store_dwordx4 v[10:11], v[4:7]
	s_nop 1
	v_lshl_add_u32 v4, v2, 7, v13
	ds_read_b128 v[4:7], v4
	v_add_u32_e32 v2, s4, v2
	v_mad_i64_i32 v[8:9], s[8:9], v2, s89, v[8:9]
	s_waitcnt lgkmcnt(0)
	flat_store_dwordx4 v[8:9], v[4:7]
	s_waitcnt lgkmcnt(0)
; #define LAS __attribute__((address_space(3)))
; __device__ __forceinline__ void tr64_item(const float* W, int K, int N, int srccol, bf16* WT, int destrow0  , int k0, LAS unsigned char* scr, int lane) {
;     const float* src = W + (size_t)k0 * N + (srccol >= 0 ? srccol : 0);
; #pragma unroll
;     for (int h = 0; h < 2; ++h) { float v[32];
; #pragma unroll
;         for (int i = 0; i < 32; ++i) v[i] = srccol >= 0 ? src[(size_t)(32 * h + i) * N] : 0.f;
; __device__ __forceinline__ void conv_item(const float* w_in, const float* w_out, const float* w_gate, const float* w_up, const float* w_down, unsigned char* ws, int layer, int r, LAS unsigned char* scr, int lane) {
;     ...
;         if (r < I_GU) { const int nblk = NGU / 64, kb = r / nblk, nb = r % nblk, n0 = nb * 64, pn = n0 >> 8, w0 = n0 & 255;
;             const float* W = (w0 < 128 ? w_gate : w_up) + (size_t)layer * DM * DFF;
;             tr64_item(W, DM, DFF, pn * 128 + (w0 & 127) + lane, (bf16*)(wl + W_GU), n0, kb * 64, scr, lane); return; }
.LBB0_1023:
	s_and_b64 vcc, exec, s[24:25]
	s_cbranch_vccz .LBB0_1427
	s_add_i32 s4, s6, 0xf000
	s_and_b32 s7, s4, 0xffff
	s_mul_i32 s7, s7, 0xba2f
	s_lshr_b32 s7, s7, 23
	s_mul_i32 s8, s7, 0xb0
	s_sub_i32 s8, s4, s8
	s_and_b32 s9, s8, 0xffff
	s_lshl_b32 s4, s9, 6
	s_bitcmp0_b32 s8, 1
	s_waitcnt lgkmcnt(0)
	s_cselect_b32 s10, s16, s22
	s_cselect_b32 s8, s17, s23
	s_add_u32 s10, s10, s37
	s_addc_u32 s11, s8, s36
	s_lshl_b32 s8, s9, 5
	s_and_b32 s8, s8, 0x1f80
	s_and_b32 s9, s4, 64
	s_or_b32 s8, s8, s9
	v_add_u32_e32 v2, s8, v1
	s_mul_i32 s8, s7, 0x160000
	s_add_u32 s8, s10, s8
	v_cmp_lt_i32_e64 s[40:41], -1, v2
	s_addc_u32 s9, s11, 0
	v_mov_b32_e32 v7, 0
	v_cndmask_b32_e64 v2, 0, v2, s[40:41]
	v_lshl_add_u64 v[4:5], v[2:3], 2, s[8:9]
	v_mov_b32_e32 v2, 0
	s_cmp_eq_u64 s[40:41], exec
	s_cbranch_scc1 .Lmy_cv1_nz
	v_mov_b32_e32 v146, 0
	v_mov_b32_e32 v147, 0
	v_mov_b32_e32 v148, 0
	v_mov_b32_e32 v149, 0
	v_mov_b32_e32 v150, 0
	v_mov_b32_e32 v151, 0
	v_mov_b32_e32 v152, 0
	v_mov_b32_e32 v153, 0
	v_mov_b32_e32 v154, 0
	v_mov_b32_e32 v155, 0
	v_mov_b32_e32 v156, 0
	v_mov_b32_e32 v157, 0
	v_mov_b32_e32 v158, 0
	v_mov_b32_e32 v159, 0
	v_mov_b32_e32 v160, 0
	v_mov_b32_e32 v161, 0
	v_mov_b32_e32 v162, 0
	v_mov_b32_e32 v163, 0
	v_mov_b32_e32 v164, 0
	v_mov_b32_e32 v165, 0
	v_mov_b32_e32 v166, 0
	v_mov_b32_e32 v167, 0
	v_mov_b32_e32 v168, 0
	v_mov_b32_e32 v169, 0
	v_mov_b32_e32 v170, 0
	v_mov_b32_e32 v171, 0
	v_mov_b32_e32 v172, 0
	v_mov_b32_e32 v173, 0
	v_mov_b32_e32 v174, 0
	v_mov_b32_e32 v175, 0
	v_mov_b32_e32 v176, 0
	v_mov_b32_e32 v177, 0
	v_mov_b32_e32 v8, 0
	v_mov_b32_e32 v7, 0
	v_mov_b32_e32 v10, 0
	v_mov_b32_e32 v9, 0
	v_mov_b32_e32 v12, 0
	v_mov_b32_e32 v11, 0
	v_mov_b32_e32 v14, 0
	v_mov_b32_e32 v13, 0
	v_mov_b32_e32 v16, 0
	v_mov_b32_e32 v15, 0
	v_mov_b32_e32 v18, 0
	v_mov_b32_e32 v17, 0
	v_mov_b32_e32 v20, 0
	v_mov_b32_e32 v19, 0
	v_mov_b32_e32 v22, 0
	v_mov_b32_e32 v21, 0
	v_mov_b32_e32 v24, 0
	v_mov_b32_e32 v23, 0
	v_mov_b32_e32 v26, 0
	v_mov_b32_e32 v25, 0
	v_mov_b32_e32 v28, 0
	v_mov_b32_e32 v27, 0
	v_mov_b32_e32 v30, 0
	v_mov_b32_e32 v29, 0
	v_mov_b32_e32 v32, 0
	v_mov_b32_e32 v31, 0
	v_mov_b32_e32 v34, 0
	v_mov_b32_e32 v33, 0
	v_mov_b32_e32 v36, 0
	v_mov_b32_e32 v35, 0
	v_mov_b32_e32 v38, 0
	v_mov_b32_e32 v37, 0
.Lmy_cv1_nz:
	v_mov_b64_e32 v[178:179], v[4:5]
	v_mov_b32_e32 v214, 0x5800
	v_mov_b32_e32 v215, 0
	s_and_saveexec_b64 s[16:17], s[40:41]
	global_load_dword v146, v[178:179], off
	v_lshl_add_u64 v[178:179], v[178:179], 0, v[214:215]
	global_load_dword v147, v[178:179], off
	v_lshl_add_u64 v[178:179], v[178:179], 0, v[214:215]
	global_load_dword v148, v[178:179], off
	v_lshl_add_u64 v[178:179], v[178:179], 0, v[214:215]
	global_load_dword v149, v[178:179], off
	v_lshl_add_u64 v[178:179], v[178:179], 0, v[214:215]
	global_load_dword v150, v[178:179], off
	v_lshl_add_u64 v[178:179], v[178:179], 0, v[214:215]
	global_load_dword v151, v[178:179], off
	v_lshl_add_u64 v[178:179], v[178:179], 0, v[214:215]
	global_load_dword v152, v[178:179], off
	v_lshl_add_u64 v[178:179], v[178:179], 0, v[214:215]
	global_load_dword v153, v[178:179], off
	v_lshl_add_u64 v[178:179], v[178:179], 0, v[214:215]
	global_load_dword v154, v[178:179], off
	v_lshl_add_u64 v[178:179], v[178:179], 0, v[214:215]
	global_load_dword v155, v[178:179], off
	v_lshl_add_u64 v[178:179], v[178:179], 0, v[214:215]
	global_load_dword v156, v[178:179], off
	v_lshl_add_u64 v[178:179], v[178:179], 0, v[214:215]
	global_load_dword v157, v[178:179], off
	v_lshl_add_u64 v[178:179], v[178:179], 0, v[214:215]
	global_load_dword v158, v[178:179], off
	v_lshl_add_u64 v[178:179], v[178:179], 0, v[214:215]
	global_load_dword v159, v[178:179], off
	v_lshl_add_u64 v[178:179], v[178:179], 0, v[214:215]
	global_load_dword v160, v[178:179], off
	v_lshl_add_u64 v[178:179], v[178:179], 0, v[214:215]
	global_load_dword v161, v[178:179], off
	v_lshl_add_u64 v[178:179], v[178:179], 0, v[214:215]
	global_load_dword v162, v[178:179], off
	v_lshl_add_u64 v[178:179], v[178:179], 0, v[214:215]
	global_load_dword v163, v[178:179], off
	v_lshl_add_u64 v[178:179], v[178:179], 0, v[214:215]
	global_load_dword v164, v[178:179], off
	v_lshl_add_u64 v[178:179], v[178:179], 0, v[214:215]
	global_load_dword v165, v[178:179], off
	v_lshl_add_u64 v[178:179], v[178:179], 0, v[214:215]
	global_load_dword v166, v[178:179], off
	v_lshl_add_u64 v[178:179], v[178:179], 0, v[214:215]
	global_load_dword v167, v[178:179], off
	v_lshl_add_u64 v[178:179], v[178:179], 0, v[214:215]
	global_load_dword v168, v[178:179], off
	v_lshl_add_u64 v[178:179], v[178:179], 0, v[214:215]
	global_load_dword v169, v[178:179], off
	v_lshl_add_u64 v[178:179], v[178:179], 0, v[214:215]
	global_load_dword v170, v[178:179], off
	v_lshl_add_u64 v[178:179], v[178:179], 0, v[214:215]
	global_load_dword v171, v[178:179], off
	v_lshl_add_u64 v[178:179], v[178:179], 0, v[214:215]
	global_load_dword v172, v[178:179], off
	v_lshl_add_u64 v[178:179], v[178:179], 0, v[214:215]
	global_load_dword v173, v[178:179], off
	v_lshl_add_u64 v[178:179], v[178:179], 0, v[214:215]
	global_load_dword v174, v[178:179], off
	v_lshl_add_u64 v[178:179], v[178:179], 0, v[214:215]
	global_load_dword v175, v[178:179], off
	v_lshl_add_u64 v[178:179], v[178:179], 0, v[214:215]
	global_load_dword v176, v[178:179], off
	v_lshl_add_u64 v[178:179], v[178:179], 0, v[214:215]
	global_load_dword v177, v[178:179], off
	v_lshl_add_u64 v[178:179], v[178:179], 0, v[214:215]
	global_load_dword v8, v[178:179], off
	v_lshl_add_u64 v[178:179], v[178:179], 0, v[214:215]
	global_load_dword v7, v[178:179], off
	v_lshl_add_u64 v[178:179], v[178:179], 0, v[214:215]
; #define LAS __attribute__((address_space(3)))
; __device__ __forceinline__ unsigned pk2(float lo, float hi) { pk2_f2_t v = {lo, hi}; pk2_b2_t b = __builtin_convertvector(v, pk2_b2_t); return __builtin_bit_cast(unsigned, b); }
; __device__ __forceinline__ void tr64_item(const float* W, int K, int N, int srccol, bf16* WT, int destrow0  , int k0, LAS unsigned char* scr, int lane) {
;     ...
;     for (int h = 0; h < 2; ++h) { float v[32];
; #pragma unroll
;         for (int i = 0; i < 32; ++i) v[i] = srccol >= 0 ? src[(size_t)(32 * h + i) * N] : 0.f;
; #pragma unroll
;         for (int c = 0; c < 4; ++c) { v4u o; o.x = pk2(v[8 * c], v[8 * c + 1]); o.y = pk2(v[8 * c + 2], v[8 * c + 3]); o.z = pk2(v[8 * c + 4], v[8 * c + 5]); o.w = pk2(v[8 * c + 6], v[8 * c + 7]);
;             *(LAS v4u*)(scr + lane * 128 + (((4 * h + c) ^ (lane & 7)) << 4)) = o; } }
	global_load_dword v10, v[178:179], off
	v_lshl_add_u64 v[178:179], v[178:179], 0, v[214:215]
	global_load_dword v9, v[178:179], off
	v_lshl_add_u64 v[178:179], v[178:179], 0, v[214:215]
	global_load_dword v12, v[178:179], off
	v_lshl_add_u64 v[178:179], v[178:179], 0, v[214:215]
	global_load_dword v11, v[178:179], off
	v_lshl_add_u64 v[178:179], v[178:179], 0, v[214:215]
	global_load_dword v14, v[178:179], off
	v_lshl_add_u64 v[178:179], v[178:179], 0, v[214:215]
	global_load_dword v13, v[178:179], off
	v_lshl_add_u64 v[178:179], v[178:179], 0, v[214:215]
	global_load_dword v16, v[178:179], off
	v_lshl_add_u64 v[178:179], v[178:179], 0, v[214:215]
	global_load_dword v15, v[178:179], off
	v_lshl_add_u64 v[178:179], v[178:179], 0, v[214:215]
	global_load_dword v18, v[178:179], off
	v_lshl_add_u64 v[178:179], v[178:179], 0, v[214:215]
	global_load_dword v17, v[178:179], off
	v_lshl_add_u64 v[178:179], v[178:179], 0, v[214:215]
	global_load_dword v20, v[178:179], off
	v_lshl_add_u64 v[178:179], v[178:179], 0, v[214:215]
	global_load_dword v19, v[178:179], off
	v_lshl_add_u64 v[178:179], v[178:179], 0, v[214:215]
	global_load_dword v22, v[178:179], off
	v_lshl_add_u64 v[178:179], v[178:179], 0, v[214:215]
	global_load_dword v21, v[178:179], off
	v_lshl_add_u64 v[178:179], v[178:179], 0, v[214:215]
	global_load_dword v24, v[178:179], off
	v_lshl_add_u64 v[178:179], v[178:179], 0, v[214:215]
	global_load_dword v23, v[178:179], off
	v_lshl_add_u64 v[178:179], v[178:179], 0, v[214:215]
	global_load_dword v26, v[178:179], off
	v_lshl_add_u64 v[178:179], v[178:179], 0, v[214:215]
	global_load_dword v25, v[178:179], off
	v_lshl_add_u64 v[178:179], v[178:179], 0, v[214:215]
	global_load_dword v28, v[178:179], off
	v_lshl_add_u64 v[178:179], v[178:179], 0, v[214:215]
	global_load_dword v27, v[178:179], off
	v_lshl_add_u64 v[178:179], v[178:179], 0, v[214:215]
	global_load_dword v30, v[178:179], off
	v_lshl_add_u64 v[178:179], v[178:179], 0, v[214:215]
	global_load_dword v29, v[178:179], off
	v_lshl_add_u64 v[178:179], v[178:179], 0, v[214:215]
	global_load_dword v32, v[178:179], off
	v_lshl_add_u64 v[178:179], v[178:179], 0, v[214:215]
	global_load_dword v31, v[178:179], off
	v_lshl_add_u64 v[178:179], v[178:179], 0, v[214:215]
	global_load_dword v34, v[178:179], off
	v_lshl_add_u64 v[178:179], v[178:179], 0, v[214:215]
	global_load_dword v33, v[178:179], off
	v_lshl_add_u64 v[178:179], v[178:179], 0, v[214:215]
	global_load_dword v36, v[178:179], off
	v_lshl_add_u64 v[178:179], v[178:179], 0, v[214:215]
	global_load_dword v35, v[178:179], off
	v_lshl_add_u64 v[178:179], v[178:179], 0, v[214:215]
	global_load_dword v38, v[178:179], off
	v_lshl_add_u64 v[178:179], v[178:179], 0, v[214:215]
	global_load_dword v37, v[178:179], off
	s_or_b64 exec, exec, s[16:17]
	s_waitcnt vmcnt(32)
	v_lshlrev_b32_e32 v2, 4, v1
	v_lshl_add_u32 v6, v1, 7, s46
	v_and_b32_e32 v2, 0x70, v2
	v_cvt_pk_bf16_f32 v180, v146, v147
	v_cvt_pk_bf16_f32 v181, v148, v149
	v_cvt_pk_bf16_f32 v182, v150, v151
	v_cvt_pk_bf16_f32 v183, v152, v153
	v_add_u32_e32 v184, v6, v2
	ds_write_b128 v184, v[180:183]
	v_cvt_pk_bf16_f32 v180, v154, v155
	v_cvt_pk_bf16_f32 v181, v156, v157
	v_cvt_pk_bf16_f32 v182, v158, v159
	v_cvt_pk_bf16_f32 v183, v160, v161
	v_xad_u32 v184, v2, 16, v6
	ds_write_b128 v184, v[180:183]
	v_cvt_pk_bf16_f32 v180, v162, v163
	v_cvt_pk_bf16_f32 v181, v164, v165
	v_cvt_pk_bf16_f32 v182, v166, v167
	v_cvt_pk_bf16_f32 v183, v168, v169
	v_xad_u32 v184, v2, 32, v6
	ds_write_b128 v184, v[180:183]
	v_cvt_pk_bf16_f32 v180, v170, v171
	v_cvt_pk_bf16_f32 v181, v172, v173
	v_cvt_pk_bf16_f32 v182, v174, v175
	v_cvt_pk_bf16_f32 v183, v176, v177
	v_xad_u32 v184, v2, 48, v6
	ds_write_b128 v184, v[180:183]
	s_waitcnt vmcnt(0)
; #define LAS __attribute__((address_space(3)))
; #define LDS_WAIT() asm volatile("s_waitcnt lgkmcnt(0)" ::: "memory")
; __device__ __forceinline__ unsigned pk2(float lo, float hi) { pk2_f2_t v = {lo, hi}; pk2_b2_t b = __builtin_convertvector(v, pk2_b2_t); return __builtin_bit_cast(unsigned, b); }
; __device__ __forceinline__ void tr64_item(const float* W, int K, int N, int srccol, bf16* WT, int destrow0  , int k0, LAS unsigned char* scr, int lane) {
;     ...
;         for (int c = 0; c < 4; ++c) { v4u o; o.x = pk2(v[8 * c], v[8 * c + 1]); o.y = pk2(v[8 * c + 2], v[8 * c + 3]); o.z = pk2(v[8 * c + 4], v[8 * c + 5]); o.w = pk2(v[8 * c + 6], v[8 * c + 7]);
;             *(LAS v4u*)(scr + lane * 128 + (((4 * h + c) ^ (lane & 7)) << 4)) = o; } }
;     LDS_WAIT(); asm volatile("" ::: "memory");
;     const int r = lane >> 3, c = lane & 7;
; #pragma unroll
;     for (int j = 0; j < 8; ++j) { const int n = r + 8 * j; const v4u o = *(const LAS v4u*)(scr + n * 128 + ((c ^ (n & 7)) << 4));
;         *(v4u*)(WT + (size_t)(destrow0 + n) * K + k0 + 8 * c) = o; }
	s_waitcnt vmcnt(0) lgkmcnt(0)
	v_cvt_pk_bf16_f32 v8, v8, v7
	v_cvt_pk_bf16_f32 v9, v10, v9
	v_cvt_pk_bf16_f32 v10, v12, v11
	v_cvt_pk_bf16_f32 v11, v14, v13
	v_xad_u32 v4, v2, 64, v6
	ds_write_b128 v4, v[8:11]
	v_cvt_pk_bf16_f32 v8, v16, v15
	v_cvt_pk_bf16_f32 v9, v18, v17
	v_cvt_pk_bf16_f32 v10, v20, v19
	v_cvt_pk_bf16_f32 v11, v22, v21
	v_xad_u32 v4, v2, s92, v6
	ds_write_b128 v4, v[8:11]
	v_cvt_pk_bf16_f32 v8, v24, v23
	v_cvt_pk_bf16_f32 v9, v26, v25
	v_cvt_pk_bf16_f32 v10, v28, v27
	v_cvt_pk_bf16_f32 v11, v30, v29
	v_xad_u32 v4, v2, s81, v6
	ds_write_b128 v4, v[8:11]
	v_cvt_pk_bf16_f32 v8, v32, v31
	v_cvt_pk_bf16_f32 v9, v34, v33
	v_cvt_pk_bf16_f32 v10, v36, v35
	v_cvt_pk_bf16_f32 v11, v38, v37
	v_xad_u32 v4, v2, s85, v6
	v_ashrrev_i32_e32 v12, 3, v1
	s_lshl_b32 s7, s7, 6
	ds_write_b128 v4, v[8:11]
	v_xor_b32_e32 v4, v12, v1
	v_lshlrev_b32_e32 v4, 4, v4
	s_lshl_b32 s7, s7, 1
	v_and_b32_e32 v4, 0x70, v4
	s_add_u32 s8, s60, s7
	s_waitcnt lgkmcnt(0)
	v_add_u32_e32 v13, s46, v4
	s_addc_u32 s9, s61, 0
	v_lshl_add_u64 v[8:9], s[8:9], 0, v[2:3]
	v_lshl_add_u32 v2, v12, 7, v13
	ds_read_b128 v[4:7], v2
	v_add_u32_e32 v10, s4, v12
	v_ashrrev_i32_e32 v11, 31, v10
	v_lshlrev_b64 v[10:11], 12, v[10:11]
	v_lshl_add_u64 v[10:11], v[8:9], 0, v[10:11]
	v_add_u32_e32 v2, 8, v12
	s_waitcnt lgkmcnt(0)
	flat_store_dwordx4 v[10:11], v[4:7]
	v_add_u32_e32 v10, s4, v2
	v_ashrrev_i32_e32 v11, 31, v10
	v_lshl_add_u32 v4, v2, 7, v13
	ds_read_b128 v[4:7], v4
	v_lshlrev_b64 v[10:11], 12, v[10:11]
	v_lshl_add_u64 v[10:11], v[8:9], 0, v[10:11]
	v_add_u32_e32 v2, 16, v12
	s_mov_b64 s[24:25], 0
	s_waitcnt lgkmcnt(0)
	flat_store_dwordx4 v[10:11], v[4:7]
	v_add_u32_e32 v10, s4, v2
	v_ashrrev_i32_e32 v11, 31, v10
	v_lshl_add_u32 v4, v2, 7, v13
	ds_read_b128 v[4:7], v4
	v_lshlrev_b64 v[10:11], 12, v[10:11]
	v_lshl_add_u64 v[10:11], v[8:9], 0, v[10:11]
	v_add_u32_e32 v2, 24, v12
	s_waitcnt lgkmcnt(0)
	flat_store_dwordx4 v[10:11], v[4:7]
	v_add_u32_e32 v10, s4, v2
	s_nop 0
	v_lshl_add_u32 v4, v2, 7, v13
	ds_read_b128 v[4:7], v4
	v_ashrrev_i32_e32 v11, 31, v10
	v_lshlrev_b64 v[10:11], 12, v[10:11]
	v_lshl_add_u64 v[10:11], v[8:9], 0, v[10:11]
	v_add_u32_e32 v2, 32, v12
	s_waitcnt lgkmcnt(0)
	flat_store_dwordx4 v[10:11], v[4:7]
	v_add_u32_e32 v10, s4, v2
	v_ashrrev_i32_e32 v11, 31, v10
	v_lshl_add_u32 v4, v2, 7, v13
	ds_read_b128 v[4:7], v4
	v_lshlrev_b64 v[10:11], 12, v[10:11]
	v_lshl_add_u64 v[10:11], v[8:9], 0, v[10:11]
	v_add_u32_e32 v2, 40, v12
	s_waitcnt lgkmcnt(0)
	flat_store_dwordx4 v[10:11], v[4:7]
	v_add_u32_e32 v10, s4, v2
	s_nop 0
	v_lshl_add_u32 v4, v2, 7, v13
	ds_read_b128 v[4:7], v4
	v_ashrrev_i32_e32 v11, 31, v10
	v_lshlrev_b64 v[10:11], 12, v[10:11]
	v_lshl_add_u64 v[10:11], v[8:9], 0, v[10:11]
	v_add_u32_e32 v2, 48, v12
	s_waitcnt lgkmcnt(0)
	flat_store_dwordx4 v[10:11], v[4:7]
	v_add_u32_e32 v10, s4, v2
	v_ashrrev_i32_e32 v11, 31, v10
	v_lshl_add_u32 v4, v2, 7, v13
	ds_read_b128 v[4:7], v4
	v_lshlrev_b64 v[10:11], 12, v[10:11]
	v_lshl_add_u64 v[10:11], v[8:9], 0, v[10:11]
	v_add_u32_e32 v2, 56, v12
	s_waitcnt lgkmcnt(0)
	flat_store_dwordx4 v[10:11], v[4:7]
	v_add_u32_e32 v10, s4, v2
	s_nop 0
	v_lshl_add_u32 v4, v2, 7, v13
	ds_read_b128 v[4:7], v4
	v_ashrrev_i32_e32 v11, 31, v10
	v_lshlrev_b64 v[10:11], 12, v[10:11]
	v_lshl_add_u64 v[8:9], v[8:9], 0, v[10:11]
	s_waitcnt lgkmcnt(0)
	flat_store_dwordx4 v[8:9], v[4:7]
	s_waitcnt lgkmcnt(0)

; #define LAS __attribute__((address_space(3)))
; __device__ __forceinline__ unsigned pk2(float lo, float hi) { pk2_f2_t v = {lo, hi}; pk2_b2_t b = __builtin_convertvector(v, pk2_b2_t); return __builtin_bit_cast(unsigned, b); }
; __device__ __forceinline__ void tr64_item(const float* W, int K, int N, int srccol, bf16* WT, int destrow0  , int k0, LAS unsigned char* scr, int lane) {
;     const float* src = W + (size_t)k0 * N + (srccol >= 0 ? srccol : 0);
; #pragma unroll
;     for (int h = 0; h < 2; ++h) { float v[32];
; #pragma unroll
;         for (int i = 0; i < 32; ++i) v[i] = srccol >= 0 ? src[(size_t)(32 * h + i) * N] : 0.f;
; #pragma unroll
;         for (int c = 0; c < 4; ++c) { v4u o; o.x = pk2(v[8 * c], v[8 * c + 1]); o.y = pk2(v[8 * c + 2], v[8 * c + 3]); o.z = pk2(v[8 * c + 4], v[8 * c + 5]); o.w = pk2(v[8 * c + 6], v[8 * c + 7]);
;             *(LAS v4u*)(scr + lane * 128 + (((4 * h + c) ^ (lane & 7)) << 4)) = o; } }
.LBB0_1154:
	s_waitcnt lgkmcnt(0)
	s_add_u32 s7, s14, s42
	s_addc_u32 s10, s15, s43
	s_and_b32 s8, s65, 0x1fc0
	s_and_b32 s4, s64, 0x7c0
	s_add_i32 s18, s8, 0xffffe800
	v_add_u32_e32 v2, s4, v1
	s_lshl_b64 s[8:9], s[18:19], 13
	s_add_u32 s8, s7, s8
	v_cmp_lt_i32_e64 s[40:41], -1, v2
	s_addc_u32 s9, s10, s9
	v_mov_b32_e32 v7, 0
	v_cndmask_b32_e64 v2, 0, v2, s[40:41]
	v_lshl_add_u64 v[4:5], v[2:3], 2, s[8:9]
	v_mov_b32_e32 v2, 0
	s_cmp_eq_u64 s[40:41], exec
	s_cbranch_scc1 .Lmy_cv2_nz
	v_mov_b32_e32 v146, 0
	v_mov_b32_e32 v147, 0
	v_mov_b32_e32 v148, 0
	v_mov_b32_e32 v149, 0
	v_mov_b32_e32 v150, 0
	v_mov_b32_e32 v151, 0
	v_mov_b32_e32 v152, 0
	v_mov_b32_e32 v153, 0
	v_mov_b32_e32 v154, 0
	v_mov_b32_e32 v155, 0
	v_mov_b32_e32 v156, 0
	v_mov_b32_e32 v157, 0
	v_mov_b32_e32 v158, 0
	v_mov_b32_e32 v159, 0
	v_mov_b32_e32 v160, 0
	v_mov_b32_e32 v161, 0
	v_mov_b32_e32 v162, 0
	v_mov_b32_e32 v163, 0
	v_mov_b32_e32 v164, 0
	v_mov_b32_e32 v165, 0
	v_mov_b32_e32 v166, 0
	v_mov_b32_e32 v167, 0
	v_mov_b32_e32 v168, 0
	v_mov_b32_e32 v169, 0
	v_mov_b32_e32 v170, 0
	v_mov_b32_e32 v171, 0
	v_mov_b32_e32 v172, 0
	v_mov_b32_e32 v173, 0
	v_mov_b32_e32 v174, 0
	v_mov_b32_e32 v175, 0
	v_mov_b32_e32 v176, 0
	v_mov_b32_e32 v177, 0
	v_mov_b32_e32 v8, 0
	v_mov_b32_e32 v7, 0
	v_mov_b32_e32 v10, 0
	v_mov_b32_e32 v9, 0
	v_mov_b32_e32 v12, 0
	v_mov_b32_e32 v11, 0
	v_mov_b32_e32 v14, 0
	v_mov_b32_e32 v13, 0
	v_mov_b32_e32 v16, 0
	v_mov_b32_e32 v15, 0
	v_mov_b32_e32 v18, 0
	v_mov_b32_e32 v17, 0
	v_mov_b32_e32 v20, 0
	v_mov_b32_e32 v19, 0
	v_mov_b32_e32 v22, 0
	v_mov_b32_e32 v21, 0
	v_mov_b32_e32 v24, 0
	v_mov_b32_e32 v23, 0
	v_mov_b32_e32 v26, 0
	v_mov_b32_e32 v25, 0
	v_mov_b32_e32 v28, 0
	v_mov_b32_e32 v27, 0
	v_mov_b32_e32 v30, 0
	v_mov_b32_e32 v29, 0
	v_mov_b32_e32 v32, 0
	v_mov_b32_e32 v31, 0
	v_mov_b32_e32 v34, 0
	v_mov_b32_e32 v33, 0
	v_mov_b32_e32 v36, 0
	v_mov_b32_e32 v35, 0
	v_mov_b32_e32 v38, 0
	v_mov_b32_e32 v37, 0
.Lmy_cv2_nz:
	v_mov_b64_e32 v[178:179], v[4:5]
	v_mov_b32_e32 v214, 0x2000
	v_mov_b32_e32 v215, 0
	s_and_saveexec_b64 s[14:15], s[40:41]
	global_load_dword v146, v[178:179], off
	v_lshl_add_u64 v[178:179], v[178:179], 0, v[214:215]
	global_load_dword v147, v[178:179], off
	v_lshl_add_u64 v[178:179], v[178:179], 0, v[214:215]
	global_load_dword v148, v[178:179], off
	v_lshl_add_u64 v[178:179], v[178:179], 0, v[214:215]
	global_load_dword v149, v[178:179], off
	v_lshl_add_u64 v[178:179], v[178:179], 0, v[214:215]
	global_load_dword v150, v[178:179], off
	v_lshl_add_u64 v[178:179], v[178:179], 0, v[214:215]
	global_load_dword v151, v[178:179], off
	v_lshl_add_u64 v[178:179], v[178:179], 0, v[214:215]
	global_load_dword v152, v[178:179], off
	v_lshl_add_u64 v[178:179], v[178:179], 0, v[214:215]
	global_load_dword v153, v[178:179], off
	v_lshl_add_u64 v[178:179], v[178:179], 0, v[214:215]
	global_load_dword v154, v[178:179], off
	v_lshl_add_u64 v[178:179], v[178:179], 0, v[214:215]
	global_load_dword v155, v[178:179], off
	v_lshl_add_u64 v[178:179], v[178:179], 0, v[214:215]
	global_load_dword v156, v[178:179], off
	v_lshl_add_u64 v[178:179], v[178:179], 0, v[214:215]
	global_load_dword v157, v[178:179], off
	v_lshl_add_u64 v[178:179], v[178:179], 0, v[214:215]
	global_load_dword v158, v[178:179], off
	v_lshl_add_u64 v[178:179], v[178:179], 0, v[214:215]
	global_load_dword v159, v[178:179], off
	v_lshl_add_u64 v[178:179], v[178:179], 0, v[214:215]
	global_load_dword v160, v[178:179], off
	v_lshl_add_u64 v[178:179], v[178:179], 0, v[214:215]
	global_load_dword v161, v[178:179], off
	v_lshl_add_u64 v[178:179], v[178:179], 0, v[214:215]
	global_load_dword v162, v[178:179], off
	v_lshl_add_u64 v[178:179], v[178:179], 0, v[214:215]
	global_load_dword v163, v[178:179], off
	v_lshl_add_u64 v[178:179], v[178:179], 0, v[214:215]
	global_load_dword v164, v[178:179], off
	v_lshl_add_u64 v[178:179], v[178:179], 0, v[214:215]
	global_load_dword v165, v[178:179], off
	v_lshl_add_u64 v[178:179], v[178:179], 0, v[214:215]
	global_load_dword v166, v[178:179], off
	v_lshl_add_u64 v[178:179], v[178:179], 0, v[214:215]
	global_load_dword v167, v[178:179], off
	v_lshl_add_u64 v[178:179], v[178:179], 0, v[214:215]
	global_load_dword v168, v[178:179], off
	v_lshl_add_u64 v[178:179], v[178:179], 0, v[214:215]
	global_load_dword v169, v[178:179], off
	v_lshl_add_u64 v[178:179], v[178:179], 0, v[214:215]
	global_load_dword v170, v[178:179], off
	v_lshl_add_u64 v[178:179], v[178:179], 0, v[214:215]
	global_load_dword v171, v[178:179], off
	v_lshl_add_u64 v[178:179], v[178:179], 0, v[214:215]
	global_load_dword v172, v[178:179], off
	v_lshl_add_u64 v[178:179], v[178:179], 0, v[214:215]
	global_load_dword v173, v[178:179], off
	v_lshl_add_u64 v[178:179], v[178:179], 0, v[214:215]
	global_load_dword v174, v[178:179], off
	v_lshl_add_u64 v[178:179], v[178:179], 0, v[214:215]
	global_load_dword v175, v[178:179], off
	v_lshl_add_u64 v[178:179], v[178:179], 0, v[214:215]
	global_load_dword v176, v[178:179], off
	v_lshl_add_u64 v[178:179], v[178:179], 0, v[214:215]
	global_load_dword v177, v[178:179], off
	v_lshl_add_u64 v[178:179], v[178:179], 0, v[214:215]
	global_load_dword v8, v[178:179], off
	v_lshl_add_u64 v[178:179], v[178:179], 0, v[214:215]
	global_load_dword v7, v[178:179], off
	v_lshl_add_u64 v[178:179], v[178:179], 0, v[214:215]
	global_load_dword v10, v[178:179], off
	v_lshl_add_u64 v[178:179], v[178:179], 0, v[214:215]
	global_load_dword v9, v[178:179], off
	v_lshl_add_u64 v[178:179], v[178:179], 0, v[214:215]
	global_load_dword v12, v[178:179], off
	v_lshl_add_u64 v[178:179], v[178:179], 0, v[214:215]
	global_load_dword v11, v[178:179], off
	v_lshl_add_u64 v[178:179], v[178:179], 0, v[214:215]
; #define LAS __attribute__((address_space(3)))
; #define LDS_WAIT() asm volatile("s_waitcnt lgkmcnt(0)" ::: "memory")
; __device__ __forceinline__ unsigned pk2(float lo, float hi) { pk2_f2_t v = {lo, hi}; pk2_b2_t b = __builtin_convertvector(v, pk2_b2_t); return __builtin_bit_cast(unsigned, b); }
; __device__ __forceinline__ void tr64_item(const float* W, int K, int N, int srccol, bf16* WT, int destrow0  , int k0, LAS unsigned char* scr, int lane) {
;     const float* src = W + (size_t)k0 * N + (srccol >= 0 ? srccol : 0);
; #pragma unroll
;     for (int h = 0; h < 2; ++h) { float v[32];
; #pragma unroll
;         for (int i = 0; i < 32; ++i) v[i] = srccol >= 0 ? src[(size_t)(32 * h + i) * N] : 0.f;
; #pragma unroll
;         for (int c = 0; c < 4; ++c) { v4u o; o.x = pk2(v[8 * c], v[8 * c + 1]); o.y = pk2(v[8 * c + 2], v[8 * c + 3]); o.z = pk2(v[8 * c + 4], v[8 * c + 5]); o.w = pk2(v[8 * c + 6], v[8 * c + 7]);
;             *(LAS v4u*)(scr + lane * 128 + (((4 * h + c) ^ (lane & 7)) << 4)) = o; } }
;     LDS_WAIT(); asm volatile("" ::: "memory");
;     const int r = lane >> 3, c = lane & 7;
; #pragma unroll
;     for (int j = 0; j < 8; ++j) { const int n = r + 8 * j; const v4u o = *(const LAS v4u*)(scr + n * 128 + ((c ^ (n & 7)) << 4));
;         *(v4u*)(WT + (size_t)(destrow0 + n) * K + k0 + 8 * c) = o; }
	global_load_dword v14, v[178:179], off
	v_lshl_add_u64 v[178:179], v[178:179], 0, v[214:215]
	global_load_dword v13, v[178:179], off
	v_lshl_add_u64 v[178:179], v[178:179], 0, v[214:215]
	global_load_dword v16, v[178:179], off
	v_lshl_add_u64 v[178:179], v[178:179], 0, v[214:215]
	global_load_dword v15, v[178:179], off
	v_lshl_add_u64 v[178:179], v[178:179], 0, v[214:215]
	global_load_dword v18, v[178:179], off
	v_lshl_add_u64 v[178:179], v[178:179], 0, v[214:215]
	global_load_dword v17, v[178:179], off
	v_lshl_add_u64 v[178:179], v[178:179], 0, v[214:215]
	global_load_dword v20, v[178:179], off
	v_lshl_add_u64 v[178:179], v[178:179], 0, v[214:215]
	global_load_dword v19, v[178:179], off
	v_lshl_add_u64 v[178:179], v[178:179], 0, v[214:215]
	global_load_dword v22, v[178:179], off
	v_lshl_add_u64 v[178:179], v[178:179], 0, v[214:215]
	global_load_dword v21, v[178:179], off
	v_lshl_add_u64 v[178:179], v[178:179], 0, v[214:215]
	global_load_dword v24, v[178:179], off
	v_lshl_add_u64 v[178:179], v[178:179], 0, v[214:215]
	global_load_dword v23, v[178:179], off
	v_lshl_add_u64 v[178:179], v[178:179], 0, v[214:215]
	global_load_dword v26, v[178:179], off
	v_lshl_add_u64 v[178:179], v[178:179], 0, v[214:215]
	global_load_dword v25, v[178:179], off
	v_lshl_add_u64 v[178:179], v[178:179], 0, v[214:215]
	global_load_dword v28, v[178:179], off
	v_lshl_add_u64 v[178:179], v[178:179], 0, v[214:215]
	global_load_dword v27, v[178:179], off
	v_lshl_add_u64 v[178:179], v[178:179], 0, v[214:215]
	global_load_dword v30, v[178:179], off
	v_lshl_add_u64 v[178:179], v[178:179], 0, v[214:215]
	global_load_dword v29, v[178:179], off
	v_lshl_add_u64 v[178:179], v[178:179], 0, v[214:215]
	global_load_dword v32, v[178:179], off
	v_lshl_add_u64 v[178:179], v[178:179], 0, v[214:215]
	global_load_dword v31, v[178:179], off
	v_lshl_add_u64 v[178:179], v[178:179], 0, v[214:215]
	global_load_dword v34, v[178:179], off
	v_lshl_add_u64 v[178:179], v[178:179], 0, v[214:215]
	global_load_dword v33, v[178:179], off
	v_lshl_add_u64 v[178:179], v[178:179], 0, v[214:215]
	global_load_dword v36, v[178:179], off
	v_lshl_add_u64 v[178:179], v[178:179], 0, v[214:215]
	global_load_dword v35, v[178:179], off
	v_lshl_add_u64 v[178:179], v[178:179], 0, v[214:215]
	global_load_dword v38, v[178:179], off
	v_lshl_add_u64 v[178:179], v[178:179], 0, v[214:215]
	global_load_dword v37, v[178:179], off
	s_or_b64 exec, exec, s[14:15]
	s_waitcnt vmcnt(32)
	v_lshlrev_b32_e32 v2, 4, v1
	v_lshl_add_u32 v6, v1, 7, s46
	v_and_b32_e32 v2, 0x70, v2
	v_cvt_pk_bf16_f32 v180, v146, v147
	v_cvt_pk_bf16_f32 v181, v148, v149
	v_cvt_pk_bf16_f32 v182, v150, v151
	v_cvt_pk_bf16_f32 v183, v152, v153
	v_add_u32_e32 v184, v6, v2
	ds_write_b128 v184, v[180:183]
	v_cvt_pk_bf16_f32 v180, v154, v155
	v_cvt_pk_bf16_f32 v181, v156, v157
	v_cvt_pk_bf16_f32 v182, v158, v159
	v_cvt_pk_bf16_f32 v183, v160, v161
	v_xad_u32 v184, v2, 16, v6
	ds_write_b128 v184, v[180:183]
	v_cvt_pk_bf16_f32 v180, v162, v163
	v_cvt_pk_bf16_f32 v181, v164, v165
	v_cvt_pk_bf16_f32 v182, v166, v167
	v_cvt_pk_bf16_f32 v183, v168, v169
	v_xad_u32 v184, v2, 32, v6
	ds_write_b128 v184, v[180:183]
	v_cvt_pk_bf16_f32 v180, v170, v171
	v_cvt_pk_bf16_f32 v181, v172, v173
	v_cvt_pk_bf16_f32 v182, v174, v175
	v_cvt_pk_bf16_f32 v183, v176, v177
	v_xad_u32 v184, v2, 48, v6
	ds_write_b128 v184, v[180:183]
	s_waitcnt vmcnt(0)
	s_waitcnt vmcnt(0) lgkmcnt(0)
	v_cvt_pk_bf16_f32 v8, v8, v7
	v_cvt_pk_bf16_f32 v9, v10, v9
	v_cvt_pk_bf16_f32 v10, v12, v11
	v_cvt_pk_bf16_f32 v11, v14, v13
	v_xad_u32 v4, v2, 64, v6
	ds_write_b128 v4, v[8:11]
	v_cvt_pk_bf16_f32 v8, v16, v15
	v_cvt_pk_bf16_f32 v9, v18, v17
	v_cvt_pk_bf16_f32 v10, v20, v19
	v_cvt_pk_bf16_f32 v11, v22, v21
	v_xad_u32 v4, v2, s92, v6
	ds_write_b128 v4, v[8:11]
	v_cvt_pk_bf16_f32 v8, v24, v23
	v_cvt_pk_bf16_f32 v9, v26, v25
	v_cvt_pk_bf16_f32 v10, v28, v27
	v_cvt_pk_bf16_f32 v11, v30, v29
	v_xad_u32 v4, v2, s81, v6
	ds_write_b128 v4, v[8:11]
	v_cvt_pk_bf16_f32 v8, v32, v31
	v_cvt_pk_bf16_f32 v9, v34, v33
	v_cvt_pk_bf16_f32 v10, v36, v35
	v_cvt_pk_bf16_f32 v11, v38, v37
	v_xad_u32 v4, v2, s85, v6
	v_ashrrev_i32_e32 v12, 3, v1
	ds_write_b128 v4, v[8:11]
	v_xor_b32_e32 v4, v12, v1
	v_lshlrev_b32_e32 v4, 4, v4
	s_lshl_b64 s[8:9], s[18:19], 1
	v_and_b32_e32 v4, 0x70, v4
	s_add_u32 s8, s62, s8
	s_waitcnt lgkmcnt(0)
	v_add_u32_e32 v13, s46, v4
	s_addc_u32 s9, s63, s9
	v_lshl_add_u64 v[8:9], s[8:9], 0, v[2:3]
	v_lshl_add_u32 v2, v12, 7, v13
	ds_read_b128 v[4:7], v2
	v_add_u32_e32 v10, s4, v12
	v_ashrrev_i32_e32 v11, 31, v10
	v_lshlrev_b64 v[10:11], 12, v[10:11]
	v_lshl_add_u64 v[10:11], v[8:9], 0, v[10:11]
	v_add_u32_e32 v2, 8, v12
	s_waitcnt lgkmcnt(0)
	flat_store_dwordx4 v[10:11], v[4:7]
	v_add_u32_e32 v10, s4, v2
	v_ashrrev_i32_e32 v11, 31, v10
	v_lshl_add_u32 v4, v2, 7, v13
	ds_read_b128 v[4:7], v4
	v_lshlrev_b64 v[10:11], 12, v[10:11]
	v_lshl_add_u64 v[10:11], v[8:9], 0, v[10:11]
	v_add_u32_e32 v2, 16, v12
	s_waitcnt lgkmcnt(0)
	flat_store_dwordx4 v[10:11], v[4:7]
	v_add_u32_e32 v10, s4, v2
	s_nop 0
	v_lshl_add_u32 v4, v2, 7, v13
	ds_read_b128 v[4:7], v4
	v_ashrrev_i32_e32 v11, 31, v10
	v_lshlrev_b64 v[10:11], 12, v[10:11]
	v_lshl_add_u64 v[10:11], v[8:9], 0, v[10:11]
	v_add_u32_e32 v2, 24, v12
	s_waitcnt lgkmcnt(0)
	flat_store_dwordx4 v[10:11], v[4:7]
	v_add_u32_e32 v10, s4, v2
	v_ashrrev_i32_e32 v11, 31, v10
	v_lshl_add_u32 v4, v2, 7, v13
	ds_read_b128 v[4:7], v4
	v_lshlrev_b64 v[10:11], 12, v[10:11]
	v_lshl_add_u64 v[10:11], v[8:9], 0, v[10:11]
	v_add_u32_e32 v2, 32, v12
	s_waitcnt lgkmcnt(0)
	flat_store_dwordx4 v[10:11], v[4:7]
	v_add_u32_e32 v10, s4, v2
	s_nop 0
	v_lshl_add_u32 v4, v2, 7, v13
	ds_read_b128 v[4:7], v4
	v_ashrrev_i32_e32 v11, 31, v10
	v_lshlrev_b64 v[10:11], 12, v[10:11]
	v_lshl_add_u64 v[10:11], v[8:9], 0, v[10:11]
	v_add_u32_e32 v2, 40, v12
	s_waitcnt lgkmcnt(0)
	flat_store_dwordx4 v[10:11], v[4:7]
	v_add_u32_e32 v10, s4, v2
	v_ashrrev_i32_e32 v11, 31, v10
	v_lshl_add_u32 v4, v2, 7, v13
	ds_read_b128 v[4:7], v4
	v_lshlrev_b64 v[10:11], 12, v[10:11]
	v_lshl_add_u64 v[10:11], v[8:9], 0, v[10:11]
	v_add_u32_e32 v2, 48, v12
	s_waitcnt lgkmcnt(0)
	flat_store_dwordx4 v[10:11], v[4:7]
	v_add_u32_e32 v10, s4, v2
	s_nop 0
	v_lshl_add_u32 v4, v2, 7, v13
	ds_read_b128 v[4:7], v4
	v_ashrrev_i32_e32 v11, 31, v10
	v_lshlrev_b64 v[10:11], 12, v[10:11]
	v_lshl_add_u64 v[10:11], v[8:9], 0, v[10:11]
	v_add_u32_e32 v2, 56, v12
	s_waitcnt lgkmcnt(0)
	flat_store_dwordx4 v[10:11], v[4:7]
	v_add_u32_e32 v10, s4, v2
	v_ashrrev_i32_e32 v11, 31, v10
	v_lshl_add_u32 v4, v2, 7, v13
	ds_read_b128 v[4:7], v4
	v_lshlrev_b64 v[10:11], 12, v[10:11]
	v_lshl_add_u64 v[8:9], v[8:9], 0, v[10:11]
	s_waitcnt lgkmcnt(0)
	flat_store_dwordx4 v[8:9], v[4:7]
	s_waitcnt lgkmcnt(0)

; #define LAS __attribute__((address_space(3)))
; __device__ __forceinline__ unsigned pk2(float lo, float hi) { pk2_f2_t v = {lo, hi}; pk2_b2_t b = __builtin_convertvector(v, pk2_b2_t); return __builtin_bit_cast(unsigned, b); }
; __device__ __forceinline__ void tr64_item(const float* W, int K, int N, int srccol, bf16* WT, int destrow0  , int k0, LAS unsigned char* scr, int lane) {
;     const float* src = W + (size_t)k0 * N + (srccol >= 0 ? srccol : 0);
; #pragma unroll
;     for (int h = 0; h < 2; ++h) { float v[32];
; #pragma unroll
;         for (int i = 0; i < 32; ++i) v[i] = srccol >= 0 ? src[(size_t)(32 * h + i) * N] : 0.f;
; #pragma unroll
;         for (int c = 0; c < 4; ++c) { v4u o; o.x = pk2(v[8 * c], v[8 * c + 1]); o.y = pk2(v[8 * c + 2], v[8 * c + 3]); o.z = pk2(v[8 * c + 4], v[8 * c + 5]); o.w = pk2(v[8 * c + 6], v[8 * c + 7]);
;             *(LAS v4u*)(scr + lane * 128 + (((4 * h + c) ^ (lane & 7)) << 4)) = o; } }
.LBB0_1299:
	s_or_b64 exec, exec, s[14:15]
	s_add_u32 s6, s2, s48
	s_addc_u32 s3, s3, s47
	s_lshl_b32 s2, s7, 6
	s_mul_i32 s7, s7, 0x171f00
	s_mul_hi_i32 s8, s2, 0x5c7c
	s_add_u32 s6, s6, s7
	v_cmp_lt_i32_e64 s[40:41], -1, v2
	s_addc_u32 s7, s3, s8
	v_mov_b32_e32 v7, 0
	v_cndmask_b32_e64 v2, 0, v2, s[40:41]
	v_lshl_add_u64 v[4:5], v[2:3], 2, s[6:7]
	v_mov_b32_e32 v2, 0
	s_cmp_eq_u64 s[40:41], exec
	s_cbranch_scc1 .Lmy_cv3_nz
	v_mov_b32_e32 v146, 0
	v_mov_b32_e32 v147, 0
	v_mov_b32_e32 v148, 0
	v_mov_b32_e32 v149, 0
	v_mov_b32_e32 v150, 0
	v_mov_b32_e32 v151, 0
	v_mov_b32_e32 v152, 0
	v_mov_b32_e32 v153, 0
	v_mov_b32_e32 v154, 0
	v_mov_b32_e32 v155, 0
	v_mov_b32_e32 v156, 0
	v_mov_b32_e32 v157, 0
	v_mov_b32_e32 v158, 0
	v_mov_b32_e32 v159, 0
	v_mov_b32_e32 v160, 0
	v_mov_b32_e32 v161, 0
	v_mov_b32_e32 v162, 0
	v_mov_b32_e32 v163, 0
	v_mov_b32_e32 v164, 0
	v_mov_b32_e32 v165, 0
	v_mov_b32_e32 v166, 0
	v_mov_b32_e32 v167, 0
	v_mov_b32_e32 v168, 0
	v_mov_b32_e32 v169, 0
	v_mov_b32_e32 v170, 0
	v_mov_b32_e32 v171, 0
	v_mov_b32_e32 v172, 0
	v_mov_b32_e32 v173, 0
	v_mov_b32_e32 v174, 0
	v_mov_b32_e32 v175, 0
	v_mov_b32_e32 v176, 0
	v_mov_b32_e32 v177, 0
	v_mov_b32_e32 v8, 0
	v_mov_b32_e32 v7, 0
	v_mov_b32_e32 v10, 0
	v_mov_b32_e32 v9, 0
	v_mov_b32_e32 v12, 0
	v_mov_b32_e32 v11, 0
	v_mov_b32_e32 v14, 0
	v_mov_b32_e32 v13, 0
	v_mov_b32_e32 v16, 0
	v_mov_b32_e32 v15, 0
	v_mov_b32_e32 v18, 0
	v_mov_b32_e32 v17, 0
	v_mov_b32_e32 v20, 0
	v_mov_b32_e32 v19, 0
	v_mov_b32_e32 v22, 0
	v_mov_b32_e32 v21, 0
	v_mov_b32_e32 v24, 0
	v_mov_b32_e32 v23, 0
	v_mov_b32_e32 v26, 0
	v_mov_b32_e32 v25, 0
	v_mov_b32_e32 v28, 0
	v_mov_b32_e32 v27, 0
	v_mov_b32_e32 v30, 0
	v_mov_b32_e32 v29, 0
	v_mov_b32_e32 v32, 0
	v_mov_b32_e32 v31, 0
	v_mov_b32_e32 v34, 0
	v_mov_b32_e32 v33, 0
	v_mov_b32_e32 v36, 0
	v_mov_b32_e32 v35, 0
	v_mov_b32_e32 v38, 0
	v_mov_b32_e32 v37, 0
.Lmy_cv3_nz:
	v_mov_b64_e32 v[178:179], v[4:5]
	v_mov_b32_e32 v214, 0x5c7c
	v_mov_b32_e32 v215, 0
	s_and_saveexec_b64 s[14:15], s[40:41]
	global_load_dword v146, v[178:179], off
	v_lshl_add_u64 v[178:179], v[178:179], 0, v[214:215]
	global_load_dword v147, v[178:179], off
	v_lshl_add_u64 v[178:179], v[178:179], 0, v[214:215]
	global_load_dword v148, v[178:179], off
	v_lshl_add_u64 v[178:179], v[178:179], 0, v[214:215]
	global_load_dword v149, v[178:179], off
	v_lshl_add_u64 v[178:179], v[178:179], 0, v[214:215]
	global_load_dword v150, v[178:179], off
	v_lshl_add_u64 v[178:179], v[178:179], 0, v[214:215]
	global_load_dword v151, v[178:179], off
	v_lshl_add_u64 v[178:179], v[178:179], 0, v[214:215]
	global_load_dword v152, v[178:179], off
	v_lshl_add_u64 v[178:179], v[178:179], 0, v[214:215]
	global_load_dword v153, v[178:179], off
	v_lshl_add_u64 v[178:179], v[178:179], 0, v[214:215]
	global_load_dword v154, v[178:179], off
	v_lshl_add_u64 v[178:179], v[178:179], 0, v[214:215]
	global_load_dword v155, v[178:179], off
	v_lshl_add_u64 v[178:179], v[178:179], 0, v[214:215]
	global_load_dword v156, v[178:179], off
	v_lshl_add_u64 v[178:179], v[178:179], 0, v[214:215]
	global_load_dword v157, v[178:179], off
	v_lshl_add_u64 v[178:179], v[178:179], 0, v[214:215]
	global_load_dword v158, v[178:179], off
	v_lshl_add_u64 v[178:179], v[178:179], 0, v[214:215]
	global_load_dword v159, v[178:179], off
	v_lshl_add_u64 v[178:179], v[178:179], 0, v[214:215]
	global_load_dword v160, v[178:179], off
	v_lshl_add_u64 v[178:179], v[178:179], 0, v[214:215]
	global_load_dword v161, v[178:179], off
	v_lshl_add_u64 v[178:179], v[178:179], 0, v[214:215]
	global_load_dword v162, v[178:179], off
	v_lshl_add_u64 v[178:179], v[178:179], 0, v[214:215]
	global_load_dword v163, v[178:179], off
	v_lshl_add_u64 v[178:179], v[178:179], 0, v[214:215]
	global_load_dword v164, v[178:179], off
	v_lshl_add_u64 v[178:179], v[178:179], 0, v[214:215]
	global_load_dword v165, v[178:179], off
	v_lshl_add_u64 v[178:179], v[178:179], 0, v[214:215]
	global_load_dword v166, v[178:179], off
	v_lshl_add_u64 v[178:179], v[178:179], 0, v[214:215]
	global_load_dword v167, v[178:179], off
	v_lshl_add_u64 v[178:179], v[178:179], 0, v[214:215]
	global_load_dword v168, v[178:179], off
	v_lshl_add_u64 v[178:179], v[178:179], 0, v[214:215]
	global_load_dword v169, v[178:179], off
	v_lshl_add_u64 v[178:179], v[178:179], 0, v[214:215]
	global_load_dword v170, v[178:179], off
	v_lshl_add_u64 v[178:179], v[178:179], 0, v[214:215]
	global_load_dword v171, v[178:179], off
	v_lshl_add_u64 v[178:179], v[178:179], 0, v[214:215]
	global_load_dword v172, v[178:179], off
; #define LAS __attribute__((address_space(3)))
; __device__ __forceinline__ unsigned pk2(float lo, float hi) { pk2_f2_t v = {lo, hi}; pk2_b2_t b = __builtin_convertvector(v, pk2_b2_t); return __builtin_bit_cast(unsigned, b); }
; __device__ __forceinline__ void tr64_item(const float* W, int K, int N, int srccol, bf16* WT, int destrow0  , int k0, LAS unsigned char* scr, int lane) {
;     const float* src = W + (size_t)k0 * N + (srccol >= 0 ? srccol : 0);
; #pragma unroll
;     for (int h = 0; h < 2; ++h) { float v[32];
; #pragma unroll
;         for (int i = 0; i < 32; ++i) v[i] = srccol >= 0 ? src[(size_t)(32 * h + i) * N] : 0.f;
; #pragma unroll
;         for (int c = 0; c < 4; ++c) { v4u o; o.x = pk2(v[8 * c], v[8 * c + 1]); o.y = pk2(v[8 * c + 2], v[8 * c + 3]); o.z = pk2(v[8 * c + 4], v[8 * c + 5]); o.w = pk2(v[8 * c + 6], v[8 * c + 7]);
;             *(LAS v4u*)(scr + lane * 128 + (((4 * h + c) ^ (lane & 7)) << 4)) = o; } }
	v_lshl_add_u64 v[178:179], v[178:179], 0, v[214:215]
	global_load_dword v173, v[178:179], off
	v_lshl_add_u64 v[178:179], v[178:179], 0, v[214:215]
	global_load_dword v174, v[178:179], off
	v_lshl_add_u64 v[178:179], v[178:179], 0, v[214:215]
	global_load_dword v175, v[178:179], off
	v_lshl_add_u64 v[178:179], v[178:179], 0, v[214:215]
	global_load_dword v176, v[178:179], off
	v_lshl_add_u64 v[178:179], v[178:179], 0, v[214:215]
	global_load_dword v177, v[178:179], off
	v_lshl_add_u64 v[178:179], v[178:179], 0, v[214:215]
	global_load_dword v8, v[178:179], off
	v_lshl_add_u64 v[178:179], v[178:179], 0, v[214:215]
	global_load_dword v7, v[178:179], off
	v_lshl_add_u64 v[178:179], v[178:179], 0, v[214:215]
	global_load_dword v10, v[178:179], off
	v_lshl_add_u64 v[178:179], v[178:179], 0, v[214:215]
	global_load_dword v9, v[178:179], off
	v_lshl_add_u64 v[178:179], v[178:179], 0, v[214:215]
	global_load_dword v12, v[178:179], off
	v_lshl_add_u64 v[178:179], v[178:179], 0, v[214:215]
	global_load_dword v11, v[178:179], off
	v_lshl_add_u64 v[178:179], v[178:179], 0, v[214:215]
	global_load_dword v14, v[178:179], off
	v_lshl_add_u64 v[178:179], v[178:179], 0, v[214:215]
	global_load_dword v13, v[178:179], off
	v_lshl_add_u64 v[178:179], v[178:179], 0, v[214:215]
	global_load_dword v16, v[178:179], off
	v_lshl_add_u64 v[178:179], v[178:179], 0, v[214:215]
	global_load_dword v15, v[178:179], off
	v_lshl_add_u64 v[178:179], v[178:179], 0, v[214:215]
	global_load_dword v18, v[178:179], off
	v_lshl_add_u64 v[178:179], v[178:179], 0, v[214:215]
	global_load_dword v17, v[178:179], off
	v_lshl_add_u64 v[178:179], v[178:179], 0, v[214:215]
	global_load_dword v20, v[178:179], off
	v_lshl_add_u64 v[178:179], v[178:179], 0, v[214:215]
	global_load_dword v19, v[178:179], off
	v_lshl_add_u64 v[178:179], v[178:179], 0, v[214:215]
	global_load_dword v22, v[178:179], off
	v_lshl_add_u64 v[178:179], v[178:179], 0, v[214:215]
	global_load_dword v21, v[178:179], off
	v_lshl_add_u64 v[178:179], v[178:179], 0, v[214:215]
	global_load_dword v24, v[178:179], off
	v_lshl_add_u64 v[178:179], v[178:179], 0, v[214:215]
	global_load_dword v23, v[178:179], off
	v_lshl_add_u64 v[178:179], v[178:179], 0, v[214:215]
	global_load_dword v26, v[178:179], off
	v_lshl_add_u64 v[178:179], v[178:179], 0, v[214:215]
	global_load_dword v25, v[178:179], off
	v_lshl_add_u64 v[178:179], v[178:179], 0, v[214:215]
	global_load_dword v28, v[178:179], off
	v_lshl_add_u64 v[178:179], v[178:179], 0, v[214:215]
	global_load_dword v27, v[178:179], off
	v_lshl_add_u64 v[178:179], v[178:179], 0, v[214:215]
	global_load_dword v30, v[178:179], off
	v_lshl_add_u64 v[178:179], v[178:179], 0, v[214:215]
	global_load_dword v29, v[178:179], off
	v_lshl_add_u64 v[178:179], v[178:179], 0, v[214:215]
	global_load_dword v32, v[178:179], off
	v_lshl_add_u64 v[178:179], v[178:179], 0, v[214:215]
	global_load_dword v31, v[178:179], off
	v_lshl_add_u64 v[178:179], v[178:179], 0, v[214:215]
	global_load_dword v34, v[178:179], off
	v_lshl_add_u64 v[178:179], v[178:179], 0, v[214:215]
	global_load_dword v33, v[178:179], off
	v_lshl_add_u64 v[178:179], v[178:179], 0, v[214:215]
	global_load_dword v36, v[178:179], off
	v_lshl_add_u64 v[178:179], v[178:179], 0, v[214:215]
	global_load_dword v35, v[178:179], off
	v_lshl_add_u64 v[178:179], v[178:179], 0, v[214:215]
	global_load_dword v38, v[178:179], off
	v_lshl_add_u64 v[178:179], v[178:179], 0, v[214:215]
	global_load_dword v37, v[178:179], off
	s_or_b64 exec, exec, s[14:15]
	s_waitcnt vmcnt(32)
	v_lshlrev_b32_e32 v2, 4, v1
	v_lshl_add_u32 v6, v1, 7, s46
	v_and_b32_e32 v2, 0x70, v2
	v_cvt_pk_bf16_f32 v180, v146, v147
	v_cvt_pk_bf16_f32 v181, v148, v149
	v_cvt_pk_bf16_f32 v182, v150, v151
	v_cvt_pk_bf16_f32 v183, v152, v153
	v_add_u32_e32 v184, v6, v2
	ds_write_b128 v184, v[180:183]
	v_cvt_pk_bf16_f32 v180, v154, v155
	v_cvt_pk_bf16_f32 v181, v156, v157
	v_cvt_pk_bf16_f32 v182, v158, v159
	v_cvt_pk_bf16_f32 v183, v160, v161
	v_xad_u32 v184, v2, 16, v6
	ds_write_b128 v184, v[180:183]
	v_cvt_pk_bf16_f32 v180, v162, v163
	v_cvt_pk_bf16_f32 v181, v164, v165
	v_cvt_pk_bf16_f32 v182, v166, v167
	v_cvt_pk_bf16_f32 v183, v168, v169
	v_xad_u32 v184, v2, 32, v6
	ds_write_b128 v184, v[180:183]
	v_cvt_pk_bf16_f32 v180, v170, v171
	v_cvt_pk_bf16_f32 v181, v172, v173
	v_cvt_pk_bf16_f32 v182, v174, v175
	v_cvt_pk_bf16_f32 v183, v176, v177
	v_xad_u32 v184, v2, 48, v6
	ds_write_b128 v184, v[180:183]
	s_waitcnt vmcnt(0)
	s_branch .LBB0_889

; #define IDX() int tid = threadIdx.x, bid = blockIdx.x, G = gridDim.x; asm volatile("" : "+v"(tid)); asm volatile("" : "+s"(bid), "+s"(G)); \
;     const int lane = tid & 63, wave = __builtin_amdgcn_readfirstlane(tid >> 6), gw = bid * NWAVES + wave, NGW = G * NWAVES; (void)lane; (void)gw; (void)NGW; (void)wave
; #define SEAM(k) do { if (N_LAUNCH_MODE == 0 && IN(k) && IN((k) + 1)) xcd_barrier(bar); } while (0)
; __device__ __forceinline__ void xcd_barrier(const XcdBarrier& b) {
;     asm volatile("s_waitcnt vmcnt(0)" ::: "memory");
;     __syncthreads();
;     if (threadIdx.x == 0) {
;         unsigned* bar = b.bar;
;         __builtin_amdgcn_s_waitcnt(0);
;         unsigned nloc = b.st[0], nx = b.st[1];
;         if (nloc == 0u) { xcd_barrier_complete(bar, b.x, nloc, nx); b.st[0] = nloc; b.st[1] = nx; }
; template <int PHM, int ATTM> __global__ void __launch_bounds__(NWAVES * 64, 2) fwd_kernel(Args args) {
;     ...
;         if (IN(pb + 4) && EN(5)) for (int rep = 0; rep < (DUP_PHASE == 5 ? 2 : 1); ++rep, (DUP_PHASE == 5 ? xcd_barrier(bar) : (void)0)) { IDX();
;             attention_phase<ATTM>(layer, lane, rep, lds, wave); }
;         SEAM(pb + 4);
.LBB0_1428:
	v_readlane_b32 s2, v255, 21
	s_cmp_lg_u32 s2, 0
	v_readlane_b32 s3, v255, 22
	s_cbranch_scc0 .LBB0_1442
.LBB0_1429:
	s_cmp_eq_u32 s99, 1
	s_cbranch_scc0 .Lmy_cf_done
	s_mov_b32 s99, 2
	s_branch .Lmy_att_preamble
.Lmy_cf_done:
	v_readlane_b32 s2, v255, 20
	s_add_i32 s4, s2, 6
	s_cmp_ge_i32 s4, s67
	s_cbranch_scc1 .LBB0_2026
	s_waitcnt vmcnt(0)
	s_waitcnt vmcnt(0) lgkmcnt(0)
	s_barrier
	s_and_saveexec_b64 s[2:3], s[70:71]
	s_cbranch_execz .LBB0_2025
	v_readlane_b32 s5, v255, 11
	s_waitcnt vmcnt(0) expcnt(0) lgkmcnt(0)
	s_nop 0
	v_mov_b32_e32 v1, s5
	ds_read_b32 v4, v1
	v_readlane_b32 s5, v255, 12
	s_waitcnt lgkmcnt(0)
	v_cmp_ne_u32_e32 vcc, 0, v4
	v_mov_b32_e32 v1, s5
	ds_read_b32 v2, v1
	s_cbranch_vccnz .LBB0_1996
	s_load_dwordx2 s[6:7], s[72:73], 0x0
	s_load_dword s8, s[72:73], 0x8
	s_mov_b32 s5, 1
	s_mov_b64 s[14:15], 0
	s_waitcnt lgkmcnt(0)
	s_mul_i32 s6, s7, s6
	s_mul_i32 s6, s6, s8
	s_branch .LBB0_1435

; #define LAS __attribute__((address_space(3)))
; __device__ __forceinline__ unsigned pk2(float lo, float hi) { pk2_f2_t v = {lo, hi}; pk2_b2_t b = __builtin_convertvector(v, pk2_b2_t); return __builtin_bit_cast(unsigned, b); }
; __device__ __forceinline__ void tr64_item(const float* W, int K, int N, int srccol, bf16* WT, int destrow0  , int k0, LAS unsigned char* scr, int lane) {
;     const float* src = W + (size_t)k0 * N + (srccol >= 0 ? srccol : 0);
; #pragma unroll
;     for (int h = 0; h < 2; ++h) { float v[32];
; #pragma unroll
;         for (int i = 0; i < 32; ++i) v[i] = srccol >= 0 ? src[(size_t)(32 * h + i) * N] : 0.f;
; #pragma unroll
;         for (int c = 0; c < 4; ++c) { v4u o; o.x = pk2(v[8 * c], v[8 * c + 1]); o.y = pk2(v[8 * c + 2], v[8 * c + 3]); o.z = pk2(v[8 * c + 4], v[8 * c + 5]); o.w = pk2(v[8 * c + 6], v[8 * c + 7]);
;             *(LAS v4u*)(scr + lane * 128 + (((4 * h + c) ^ (lane & 7)) << 4)) = o; } }
; __device__ __forceinline__ void conv_item(const float* w_in, const float* w_out, const float* w_gate, const float* w_up, const float* w_down, unsigned char* ws, int layer, int r, LAS unsigned char* scr, int lane) {
;     {
;         unsigned char* wl = ws + WS_W + (size_t)layer * W_LAYER;
;         if (r < I_IN) { const int nblk = NINP / 64, kb = r / nblk, nb = r % nblk;
;             tr64_item(w_in + (size_t)layer * DM * NIN, DM, NIN, src_col_in(nb * 64 + lane), (bf16*)(wl + W_IN), nb * 64, kb * 64, scr, lane); return; }
;         r -= I_IN;
;         if (r < I_OUT) { const int nblk = DM / 64, kb = r / nblk, nb = r % nblk;
;             tr64_item(w_out + (size_t)layer * DM * DM, DM, DM, nb * 64 + lane, (bf16*)(wl + W_OUT), nb * 64, kb * 64, scr, lane); return; }
;         r -= I_OUT;
;         if (r < I_GU) { const int nblk = NGU / 64, kb = r / nblk, nb = r % nblk, n0 = nb * 64, pn = n0 >> 8, w0 = n0 & 255;
;             const float* W = (w0 < 128 ? w_gate : w_up) + (size_t)layer * DM * DFF;
;             tr64_item(W, DM, DFF, pn * 128 + (w0 & 127) + lane, (bf16*)(wl + W_GU), n0, kb * 64, scr, lane); return; }
;         r -= I_GU;
;         { const int nblk = DM / 64, kb = r / nblk, nb = r % nblk;
;             tr64_item(w_down + (size_t)layer * DFF * DM, DFF, DM, nb * 64 + lane, (bf16*)(wl + W_D), nb * 64, kb * 64, scr, lane); }
.LBB0_1456:
	s_waitcnt lgkmcnt(0)
	s_load_dwordx2 s[2:3], s[0:1], 0x30
	s_load_dwordx2 s[14:15], s[0:1], 0x68
	s_load_dwordx2 s[16:17], s[0:1], 0x70
	s_load_dwordx2 s[22:23], s[0:1], 0x78
	s_load_dwordx2 s[20:21], s[0:1], 0x80
	s_add_i32 s6, s27, s37
	v_mov_b32_e32 v1, v239
	s_cmpk_gt_i32 s6, 0xbff
	s_mov_b64 s[24:25], -1
	s_cbranch_scc0 .LBB0_1849
	s_cmpk_gt_u32 s6, 0xfff
	s_cbranch_scc0 .LBB0_1718
	s_cmpk_gt_u32 s6, 0x25ff
	s_cbranch_scc0 .LBB0_1588
	s_and_b32 s7, s53, 0x7fffffc0
	s_and_b32 s4, s52, 0x7c0
	s_add_i32 s18, s7, 0xffffb400
	v_add_u32_e32 v2, s4, v1
	s_lshl_b64 s[8:9], s[18:19], 13
	s_waitcnt lgkmcnt(0)
	s_add_u32 s8, s20, s8
	v_cmp_lt_i32_e64 s[40:41], -1, v2
	s_addc_u32 s9, s21, s9
	v_mov_b32_e32 v7, 0
	v_cndmask_b32_e64 v2, 0, v2, s[40:41]
	v_lshl_add_u64 v[4:5], v[2:3], 2, s[8:9]
	v_mov_b32_e32 v2, 0
	s_cmp_eq_u64 s[40:41], exec
	s_cbranch_scc1 .Lmy_cv4_nz
	v_mov_b32_e32 v146, 0
	v_mov_b32_e32 v147, 0
	v_mov_b32_e32 v148, 0
	v_mov_b32_e32 v149, 0
	v_mov_b32_e32 v150, 0
	v_mov_b32_e32 v151, 0
	v_mov_b32_e32 v152, 0
	v_mov_b32_e32 v153, 0
	v_mov_b32_e32 v154, 0
	v_mov_b32_e32 v155, 0
	v_mov_b32_e32 v156, 0
	v_mov_b32_e32 v157, 0
	v_mov_b32_e32 v158, 0
	v_mov_b32_e32 v159, 0
	v_mov_b32_e32 v160, 0
	v_mov_b32_e32 v161, 0
	v_mov_b32_e32 v162, 0
	v_mov_b32_e32 v163, 0
	v_mov_b32_e32 v164, 0
	v_mov_b32_e32 v165, 0
	v_mov_b32_e32 v166, 0
	v_mov_b32_e32 v167, 0
	v_mov_b32_e32 v168, 0
	v_mov_b32_e32 v169, 0
	v_mov_b32_e32 v170, 0
	v_mov_b32_e32 v171, 0
	v_mov_b32_e32 v172, 0
	v_mov_b32_e32 v173, 0
	v_mov_b32_e32 v174, 0
	v_mov_b32_e32 v175, 0
	v_mov_b32_e32 v176, 0
	v_mov_b32_e32 v177, 0
	v_mov_b32_e32 v8, 0
	v_mov_b32_e32 v7, 0
	v_mov_b32_e32 v10, 0
	v_mov_b32_e32 v9, 0
	v_mov_b32_e32 v12, 0
	v_mov_b32_e32 v11, 0
	v_mov_b32_e32 v14, 0
	v_mov_b32_e32 v13, 0
	v_mov_b32_e32 v16, 0
	v_mov_b32_e32 v15, 0
	v_mov_b32_e32 v18, 0
	v_mov_b32_e32 v17, 0
	v_mov_b32_e32 v20, 0
	v_mov_b32_e32 v19, 0
	v_mov_b32_e32 v22, 0
	v_mov_b32_e32 v21, 0
	v_mov_b32_e32 v24, 0
	v_mov_b32_e32 v23, 0
	v_mov_b32_e32 v26, 0
	v_mov_b32_e32 v25, 0
	v_mov_b32_e32 v28, 0
	v_mov_b32_e32 v27, 0
	v_mov_b32_e32 v30, 0
	v_mov_b32_e32 v29, 0
	v_mov_b32_e32 v32, 0
	v_mov_b32_e32 v31, 0
	v_mov_b32_e32 v34, 0
	v_mov_b32_e32 v33, 0
	v_mov_b32_e32 v36, 0
	v_mov_b32_e32 v35, 0
	v_mov_b32_e32 v38, 0
	v_mov_b32_e32 v37, 0
.Lmy_cv4_nz:
	v_mov_b64_e32 v[178:179], v[4:5]
	v_mov_b32_e32 v214, 0x2000
	v_mov_b32_e32 v215, 0
	s_and_saveexec_b64 s[20:21], s[40:41]
	global_load_dword v146, v[178:179], off
	v_lshl_add_u64 v[178:179], v[178:179], 0, v[214:215]
	global_load_dword v147, v[178:179], off
	v_lshl_add_u64 v[178:179], v[178:179], 0, v[214:215]
	global_load_dword v148, v[178:179], off
	v_lshl_add_u64 v[178:179], v[178:179], 0, v[214:215]
	global_load_dword v149, v[178:179], off
	v_lshl_add_u64 v[178:179], v[178:179], 0, v[214:215]
	global_load_dword v150, v[178:179], off
	v_lshl_add_u64 v[178:179], v[178:179], 0, v[214:215]
	global_load_dword v151, v[178:179], off
	v_lshl_add_u64 v[178:179], v[178:179], 0, v[214:215]
	global_load_dword v152, v[178:179], off
	v_lshl_add_u64 v[178:179], v[178:179], 0, v[214:215]
	global_load_dword v153, v[178:179], off
	v_lshl_add_u64 v[178:179], v[178:179], 0, v[214:215]
	global_load_dword v154, v[178:179], off
	v_lshl_add_u64 v[178:179], v[178:179], 0, v[214:215]
	global_load_dword v155, v[178:179], off
	v_lshl_add_u64 v[178:179], v[178:179], 0, v[214:215]
	global_load_dword v156, v[178:179], off
	v_lshl_add_u64 v[178:179], v[178:179], 0, v[214:215]
	global_load_dword v157, v[178:179], off
	v_lshl_add_u64 v[178:179], v[178:179], 0, v[214:215]
	global_load_dword v158, v[178:179], off
	v_lshl_add_u64 v[178:179], v[178:179], 0, v[214:215]
	global_load_dword v159, v[178:179], off
	v_lshl_add_u64 v[178:179], v[178:179], 0, v[214:215]
	global_load_dword v160, v[178:179], off
	v_lshl_add_u64 v[178:179], v[178:179], 0, v[214:215]
	global_load_dword v161, v[178:179], off
	v_lshl_add_u64 v[178:179], v[178:179], 0, v[214:215]
	global_load_dword v162, v[178:179], off
	v_lshl_add_u64 v[178:179], v[178:179], 0, v[214:215]
	global_load_dword v163, v[178:179], off
	v_lshl_add_u64 v[178:179], v[178:179], 0, v[214:215]
	global_load_dword v164, v[178:179], off
	v_lshl_add_u64 v[178:179], v[178:179], 0, v[214:215]
	global_load_dword v165, v[178:179], off
	v_lshl_add_u64 v[178:179], v[178:179], 0, v[214:215]
	global_load_dword v166, v[178:179], off
	v_lshl_add_u64 v[178:179], v[178:179], 0, v[214:215]
	global_load_dword v167, v[178:179], off
	v_lshl_add_u64 v[178:179], v[178:179], 0, v[214:215]
	global_load_dword v168, v[178:179], off
	v_lshl_add_u64 v[178:179], v[178:179], 0, v[214:215]
	global_load_dword v169, v[178:179], off
	v_lshl_add_u64 v[178:179], v[178:179], 0, v[214:215]
	global_load_dword v170, v[178:179], off
	v_lshl_add_u64 v[178:179], v[178:179], 0, v[214:215]
	global_load_dword v171, v[178:179], off
	v_lshl_add_u64 v[178:179], v[178:179], 0, v[214:215]
	global_load_dword v172, v[178:179], off
	v_lshl_add_u64 v[178:179], v[178:179], 0, v[214:215]
	global_load_dword v173, v[178:179], off
	v_lshl_add_u64 v[178:179], v[178:179], 0, v[214:215]
	global_load_dword v174, v[178:179], off
	v_lshl_add_u64 v[178:179], v[178:179], 0, v[214:215]
	global_load_dword v175, v[178:179], off
	v_lshl_add_u64 v[178:179], v[178:179], 0, v[214:215]
	global_load_dword v176, v[178:179], off
	v_lshl_add_u64 v[178:179], v[178:179], 0, v[214:215]
	global_load_dword v177, v[178:179], off
	v_lshl_add_u64 v[178:179], v[178:179], 0, v[214:215]
	global_load_dword v8, v[178:179], off
	v_lshl_add_u64 v[178:179], v[178:179], 0, v[214:215]
	global_load_dword v7, v[178:179], off
; #define LAS __attribute__((address_space(3)))
; #define LDS_WAIT() asm volatile("s_waitcnt lgkmcnt(0)" ::: "memory")
; __device__ __forceinline__ unsigned pk2(float lo, float hi) { pk2_f2_t v = {lo, hi}; pk2_b2_t b = __builtin_convertvector(v, pk2_b2_t); return __builtin_bit_cast(unsigned, b); }
; __device__ __forceinline__ void tr64_item(const float* W, int K, int N, int srccol, bf16* WT, int destrow0  , int k0, LAS unsigned char* scr, int lane) {
;     const float* src = W + (size_t)k0 * N + (srccol >= 0 ? srccol : 0);
; #pragma unroll
;     for (int h = 0; h < 2; ++h) { float v[32];
; #pragma unroll
;         for (int i = 0; i < 32; ++i) v[i] = srccol >= 0 ? src[(size_t)(32 * h + i) * N] : 0.f;
; #pragma unroll
;         for (int c = 0; c < 4; ++c) { v4u o; o.x = pk2(v[8 * c], v[8 * c + 1]); o.y = pk2(v[8 * c + 2], v[8 * c + 3]); o.z = pk2(v[8 * c + 4], v[8 * c + 5]); o.w = pk2(v[8 * c + 6], v[8 * c + 7]);
;             *(LAS v4u*)(scr + lane * 128 + (((4 * h + c) ^ (lane & 7)) << 4)) = o; } }
;     LDS_WAIT(); asm volatile("" ::: "memory");
;     const int r = lane >> 3, c = lane & 7;
; #pragma unroll
;     for (int j = 0; j < 8; ++j) { const int n = r + 8 * j; const v4u o = *(const LAS v4u*)(scr + n * 128 + ((c ^ (n & 7)) << 4));
;         *(v4u*)(WT + (size_t)(destrow0 + n) * K + k0 + 8 * c) = o; }
	v_lshl_add_u64 v[178:179], v[178:179], 0, v[214:215]
	global_load_dword v10, v[178:179], off
	v_lshl_add_u64 v[178:179], v[178:179], 0, v[214:215]
	global_load_dword v9, v[178:179], off
	v_lshl_add_u64 v[178:179], v[178:179], 0, v[214:215]
	global_load_dword v12, v[178:179], off
	v_lshl_add_u64 v[178:179], v[178:179], 0, v[214:215]
	global_load_dword v11, v[178:179], off
	v_lshl_add_u64 v[178:179], v[178:179], 0, v[214:215]
	global_load_dword v14, v[178:179], off
	v_lshl_add_u64 v[178:179], v[178:179], 0, v[214:215]
	global_load_dword v13, v[178:179], off
	v_lshl_add_u64 v[178:179], v[178:179], 0, v[214:215]
	global_load_dword v16, v[178:179], off
	v_lshl_add_u64 v[178:179], v[178:179], 0, v[214:215]
	global_load_dword v15, v[178:179], off
	v_lshl_add_u64 v[178:179], v[178:179], 0, v[214:215]
	global_load_dword v18, v[178:179], off
	v_lshl_add_u64 v[178:179], v[178:179], 0, v[214:215]
	global_load_dword v17, v[178:179], off
	v_lshl_add_u64 v[178:179], v[178:179], 0, v[214:215]
	global_load_dword v20, v[178:179], off
	v_lshl_add_u64 v[178:179], v[178:179], 0, v[214:215]
	global_load_dword v19, v[178:179], off
	v_lshl_add_u64 v[178:179], v[178:179], 0, v[214:215]
	global_load_dword v22, v[178:179], off
	v_lshl_add_u64 v[178:179], v[178:179], 0, v[214:215]
	global_load_dword v21, v[178:179], off
	v_lshl_add_u64 v[178:179], v[178:179], 0, v[214:215]
	global_load_dword v24, v[178:179], off
	v_lshl_add_u64 v[178:179], v[178:179], 0, v[214:215]
	global_load_dword v23, v[178:179], off
	v_lshl_add_u64 v[178:179], v[178:179], 0, v[214:215]
	global_load_dword v26, v[178:179], off
	v_lshl_add_u64 v[178:179], v[178:179], 0, v[214:215]
	global_load_dword v25, v[178:179], off
	v_lshl_add_u64 v[178:179], v[178:179], 0, v[214:215]
	global_load_dword v28, v[178:179], off
	v_lshl_add_u64 v[178:179], v[178:179], 0, v[214:215]
	global_load_dword v27, v[178:179], off
	v_lshl_add_u64 v[178:179], v[178:179], 0, v[214:215]
	global_load_dword v30, v[178:179], off
	v_lshl_add_u64 v[178:179], v[178:179], 0, v[214:215]
	global_load_dword v29, v[178:179], off
	v_lshl_add_u64 v[178:179], v[178:179], 0, v[214:215]
	global_load_dword v32, v[178:179], off
	v_lshl_add_u64 v[178:179], v[178:179], 0, v[214:215]
	global_load_dword v31, v[178:179], off
	v_lshl_add_u64 v[178:179], v[178:179], 0, v[214:215]
	global_load_dword v34, v[178:179], off
	v_lshl_add_u64 v[178:179], v[178:179], 0, v[214:215]
	global_load_dword v33, v[178:179], off
	v_lshl_add_u64 v[178:179], v[178:179], 0, v[214:215]
	global_load_dword v36, v[178:179], off
	v_lshl_add_u64 v[178:179], v[178:179], 0, v[214:215]
	global_load_dword v35, v[178:179], off
	v_lshl_add_u64 v[178:179], v[178:179], 0, v[214:215]
	global_load_dword v38, v[178:179], off
	v_lshl_add_u64 v[178:179], v[178:179], 0, v[214:215]
	global_load_dword v37, v[178:179], off
	s_or_b64 exec, exec, s[20:21]
	s_waitcnt vmcnt(32)
	v_lshlrev_b32_e32 v2, 4, v1
	v_lshl_add_u32 v6, v1, 7, s46
	v_and_b32_e32 v2, 0x70, v2
	v_cvt_pk_bf16_f32 v180, v146, v147
	v_cvt_pk_bf16_f32 v181, v148, v149
	v_cvt_pk_bf16_f32 v182, v150, v151
	v_cvt_pk_bf16_f32 v183, v152, v153
	v_add_u32_e32 v184, v6, v2
	ds_write_b128 v184, v[180:183]
	v_cvt_pk_bf16_f32 v180, v154, v155
	v_cvt_pk_bf16_f32 v181, v156, v157
	v_cvt_pk_bf16_f32 v182, v158, v159
	v_cvt_pk_bf16_f32 v183, v160, v161
	v_xad_u32 v184, v2, 16, v6
	ds_write_b128 v184, v[180:183]
	v_cvt_pk_bf16_f32 v180, v162, v163
	v_cvt_pk_bf16_f32 v181, v164, v165
	v_cvt_pk_bf16_f32 v182, v166, v167
	v_cvt_pk_bf16_f32 v183, v168, v169
	v_xad_u32 v184, v2, 32, v6
	ds_write_b128 v184, v[180:183]
	v_cvt_pk_bf16_f32 v180, v170, v171
	v_cvt_pk_bf16_f32 v181, v172, v173
	v_cvt_pk_bf16_f32 v182, v174, v175
	v_cvt_pk_bf16_f32 v183, v176, v177
	v_xad_u32 v184, v2, 48, v6
	ds_write_b128 v184, v[180:183]
	s_waitcnt vmcnt(0)
	s_waitcnt vmcnt(0) lgkmcnt(0)
	v_cvt_pk_bf16_f32 v8, v8, v7
	v_cvt_pk_bf16_f32 v9, v10, v9
	v_cvt_pk_bf16_f32 v10, v12, v11
	v_cvt_pk_bf16_f32 v11, v14, v13
	v_xad_u32 v4, v2, 64, v6
	ds_write_b128 v4, v[8:11]
	v_cvt_pk_bf16_f32 v8, v16, v15
	v_cvt_pk_bf16_f32 v9, v18, v17
	v_cvt_pk_bf16_f32 v10, v20, v19
	v_cvt_pk_bf16_f32 v11, v22, v21
	v_xad_u32 v4, v2, s92, v6
	ds_write_b128 v4, v[8:11]
	v_cvt_pk_bf16_f32 v8, v24, v23
	v_cvt_pk_bf16_f32 v9, v26, v25
	v_cvt_pk_bf16_f32 v10, v28, v27
	v_cvt_pk_bf16_f32 v11, v30, v29
	v_xad_u32 v4, v2, s81, v6
	ds_write_b128 v4, v[8:11]
	v_cvt_pk_bf16_f32 v8, v32, v31
	v_cvt_pk_bf16_f32 v9, v34, v33
	v_cvt_pk_bf16_f32 v10, v36, v35
	v_cvt_pk_bf16_f32 v11, v38, v37
	v_xad_u32 v4, v2, s85, v6
	v_ashrrev_i32_e32 v12, 3, v1
	ds_write_b128 v4, v[8:11]
	v_xor_b32_e32 v4, v12, v1
	v_lshlrev_b32_e32 v4, 4, v4
	v_and_b32_e32 v4, 0x70, v4
	s_waitcnt lgkmcnt(0)
	v_add_u32_e32 v13, s46, v4
	v_lshl_add_u32 v4, v12, 7, v13
	s_lshl_b64 s[8:9], s[18:19], 1
	ds_read_b128 v[4:7], v4
	s_add_u32 s8, s45, s8
	s_addc_u32 s9, s47, s9
	v_lshl_add_u64 v[8:9], s[8:9], 0, v[2:3]
	v_add_u32_e32 v2, s4, v12
	v_mad_i64_i32 v[10:11], s[8:9], v2, s89, v[8:9]
	v_add_u32_e32 v2, 8, v12
	s_waitcnt lgkmcnt(0)
	flat_store_dwordx4 v[10:11], v[4:7]
	s_mov_b64 s[24:25], 0
	s_nop 0
	v_lshl_add_u32 v4, v2, 7, v13
	ds_read_b128 v[4:7], v4
	v_add_u32_e32 v2, s4, v2
	v_mad_i64_i32 v[10:11], s[8:9], v2, s89, v[8:9]
	v_add_u32_e32 v2, 16, v12
	s_waitcnt lgkmcnt(0)
	flat_store_dwordx4 v[10:11], v[4:7]
	s_nop 1
	v_lshl_add_u32 v4, v2, 7, v13
	ds_read_b128 v[4:7], v4
	v_add_u32_e32 v2, s4, v2
	v_mad_i64_i32 v[10:11], s[8:9], v2, s89, v[8:9]
	v_add_u32_e32 v2, 24, v12
	s_waitcnt lgkmcnt(0)
	flat_store_dwordx4 v[10:11], v[4:7]
	s_nop 1
	v_lshl_add_u32 v4, v2, 7, v13
	ds_read_b128 v[4:7], v4
	v_add_u32_e32 v2, s4, v2
	v_mad_i64_i32 v[10:11], s[8:9], v2, s89, v[8:9]
	v_add_u32_e32 v2, 32, v12
	s_waitcnt lgkmcnt(0)
	flat_store_dwordx4 v[10:11], v[4:7]
	s_nop 1
	v_lshl_add_u32 v4, v2, 7, v13
	ds_read_b128 v[4:7], v4
	v_add_u32_e32 v2, s4, v2
	v_mad_i64_i32 v[10:11], s[8:9], v2, s89, v[8:9]
	v_add_u32_e32 v2, 40, v12
	s_waitcnt lgkmcnt(0)
	flat_store_dwordx4 v[10:11], v[4:7]
	s_nop 1
	v_lshl_add_u32 v4, v2, 7, v13
	ds_read_b128 v[4:7], v4
	v_add_u32_e32 v2, s4, v2
	v_mad_i64_i32 v[10:11], s[8:9], v2, s89, v[8:9]
	v_add_u32_e32 v2, 48, v12
	s_waitcnt lgkmcnt(0)
	flat_store_dwordx4 v[10:11], v[4:7]
	s_nop 1
	v_lshl_add_u32 v4, v2, 7, v13
	ds_read_b128 v[4:7], v4
	v_add_u32_e32 v2, s4, v2
	v_mad_i64_i32 v[10:11], s[8:9], v2, s89, v[8:9]
	v_add_u32_e32 v2, 56, v12
	s_waitcnt lgkmcnt(0)
	flat_store_dwordx4 v[10:11], v[4:7]
	s_nop 1
	v_lshl_add_u32 v4, v2, 7, v13
	ds_read_b128 v[4:7], v4
	v_add_u32_e32 v2, s4, v2
	v_mad_i64_i32 v[8:9], s[8:9], v2, s89, v[8:9]
	s_waitcnt lgkmcnt(0)
	flat_store_dwordx4 v[8:9], v[4:7]
	s_waitcnt lgkmcnt(0)
; #define LAS __attribute__((address_space(3)))
; __device__ __forceinline__ unsigned pk2(float lo, float hi) { pk2_f2_t v = {lo, hi}; pk2_b2_t b = __builtin_convertvector(v, pk2_b2_t); return __builtin_bit_cast(unsigned, b); }
; __device__ __forceinline__ void tr64_item(const float* W, int K, int N, int srccol, bf16* WT, int destrow0  , int k0, LAS unsigned char* scr, int lane) {
;     const float* src = W + (size_t)k0 * N + (srccol >= 0 ? srccol : 0);
; #pragma unroll
;     for (int h = 0; h < 2; ++h) { float v[32];
; #pragma unroll
;         for (int i = 0; i < 32; ++i) v[i] = srccol >= 0 ? src[(size_t)(32 * h + i) * N] : 0.f;
; #pragma unroll
;         for (int c = 0; c < 4; ++c) { v4u o; o.x = pk2(v[8 * c], v[8 * c + 1]); o.y = pk2(v[8 * c + 2], v[8 * c + 3]); o.z = pk2(v[8 * c + 4], v[8 * c + 5]); o.w = pk2(v[8 * c + 6], v[8 * c + 7]);
;             *(LAS v4u*)(scr + lane * 128 + (((4 * h + c) ^ (lane & 7)) << 4)) = o; } }
; __device__ __forceinline__ void conv_item(const float* w_in, const float* w_out, const float* w_gate, const float* w_up, const float* w_down, unsigned char* ws, int layer, int r, LAS unsigned char* scr, int lane) {
;     ...
;         if (r < I_GU) { const int nblk = NGU / 64, kb = r / nblk, nb = r % nblk, n0 = nb * 64, pn = n0 >> 8, w0 = n0 & 255;
;             const float* W = (w0 < 128 ? w_gate : w_up) + (size_t)layer * DM * DFF;
;             tr64_item(W, DM, DFF, pn * 128 + (w0 & 127) + lane, (bf16*)(wl + W_GU), n0, kb * 64, scr, lane); return; }
.LBB0_1588:
	s_and_b64 vcc, exec, s[24:25]
	s_cbranch_vccz .LBB0_1992
	s_add_i32 s4, s6, 0xf000
	s_and_b32 s7, s4, 0xffff
	s_mul_i32 s7, s7, 0xba2f
	s_lshr_b32 s7, s7, 23
	s_mul_i32 s8, s7, 0xb0
	s_sub_i32 s8, s4, s8
	s_and_b32 s9, s8, 0xffff
	s_lshl_b32 s4, s9, 6
	s_bitcmp0_b32 s8, 1
	s_waitcnt lgkmcnt(0)
	s_cselect_b32 s10, s17, s23
	s_cselect_b32 s8, s16, s22
	s_lshl_b32 s9, s9, 5
	s_and_b32 s9, s9, 0x1f80
	s_and_b32 s11, s4, 64
	s_or_b32 s9, s9, s11
	v_add_u32_e32 v2, s9, v1
	s_mul_i32 s9, s7, 0x160000
	s_add_u32 s8, s8, s9
	v_cmp_lt_i32_e64 s[40:41], -1, v2
	s_addc_u32 s9, s10, 0
	v_mov_b32_e32 v7, 0
	v_cndmask_b32_e64 v2, 0, v2, s[40:41]
	v_lshl_add_u64 v[4:5], v[2:3], 2, s[8:9]
	v_mov_b32_e32 v2, 0
	s_cmp_eq_u64 s[40:41], exec
	s_cbranch_scc1 .Lmy_cv5_nz
	v_mov_b32_e32 v146, 0
	v_mov_b32_e32 v147, 0
	v_mov_b32_e32 v148, 0
	v_mov_b32_e32 v149, 0
	v_mov_b32_e32 v150, 0
	v_mov_b32_e32 v151, 0
	v_mov_b32_e32 v152, 0
	v_mov_b32_e32 v153, 0
	v_mov_b32_e32 v154, 0
	v_mov_b32_e32 v155, 0
	v_mov_b32_e32 v156, 0
	v_mov_b32_e32 v157, 0
	v_mov_b32_e32 v158, 0
	v_mov_b32_e32 v159, 0
	v_mov_b32_e32 v160, 0
	v_mov_b32_e32 v161, 0
	v_mov_b32_e32 v162, 0
	v_mov_b32_e32 v163, 0
	v_mov_b32_e32 v164, 0
	v_mov_b32_e32 v165, 0
	v_mov_b32_e32 v166, 0
	v_mov_b32_e32 v167, 0
	v_mov_b32_e32 v168, 0
	v_mov_b32_e32 v169, 0
	v_mov_b32_e32 v170, 0
	v_mov_b32_e32 v171, 0
	v_mov_b32_e32 v172, 0
	v_mov_b32_e32 v173, 0
	v_mov_b32_e32 v174, 0
	v_mov_b32_e32 v175, 0
	v_mov_b32_e32 v176, 0
	v_mov_b32_e32 v177, 0
	v_mov_b32_e32 v8, 0
	v_mov_b32_e32 v7, 0
	v_mov_b32_e32 v10, 0
	v_mov_b32_e32 v9, 0
	v_mov_b32_e32 v12, 0
	v_mov_b32_e32 v11, 0
	v_mov_b32_e32 v14, 0
	v_mov_b32_e32 v13, 0
	v_mov_b32_e32 v16, 0
	v_mov_b32_e32 v15, 0
	v_mov_b32_e32 v18, 0
	v_mov_b32_e32 v17, 0
	v_mov_b32_e32 v20, 0
	v_mov_b32_e32 v19, 0
	v_mov_b32_e32 v22, 0
	v_mov_b32_e32 v21, 0
	v_mov_b32_e32 v24, 0
	v_mov_b32_e32 v23, 0
	v_mov_b32_e32 v26, 0
	v_mov_b32_e32 v25, 0
	v_mov_b32_e32 v28, 0
	v_mov_b32_e32 v27, 0
	v_mov_b32_e32 v30, 0
	v_mov_b32_e32 v29, 0
	v_mov_b32_e32 v32, 0
	v_mov_b32_e32 v31, 0
	v_mov_b32_e32 v34, 0
	v_mov_b32_e32 v33, 0
	v_mov_b32_e32 v36, 0
	v_mov_b32_e32 v35, 0
	v_mov_b32_e32 v38, 0
	v_mov_b32_e32 v37, 0
.Lmy_cv5_nz:
	v_mov_b64_e32 v[178:179], v[4:5]
	v_mov_b32_e32 v214, 0x5800
	v_mov_b32_e32 v215, 0
	s_and_saveexec_b64 s[16:17], s[40:41]
	global_load_dword v146, v[178:179], off
	v_lshl_add_u64 v[178:179], v[178:179], 0, v[214:215]
	global_load_dword v147, v[178:179], off
	v_lshl_add_u64 v[178:179], v[178:179], 0, v[214:215]
	global_load_dword v148, v[178:179], off
	v_lshl_add_u64 v[178:179], v[178:179], 0, v[214:215]
	global_load_dword v149, v[178:179], off
	v_lshl_add_u64 v[178:179], v[178:179], 0, v[214:215]
	global_load_dword v150, v[178:179], off
	v_lshl_add_u64 v[178:179], v[178:179], 0, v[214:215]
	global_load_dword v151, v[178:179], off
	v_lshl_add_u64 v[178:179], v[178:179], 0, v[214:215]
	global_load_dword v152, v[178:179], off
	v_lshl_add_u64 v[178:179], v[178:179], 0, v[214:215]
	global_load_dword v153, v[178:179], off
	v_lshl_add_u64 v[178:179], v[178:179], 0, v[214:215]
	global_load_dword v154, v[178:179], off
	v_lshl_add_u64 v[178:179], v[178:179], 0, v[214:215]
	global_load_dword v155, v[178:179], off
	v_lshl_add_u64 v[178:179], v[178:179], 0, v[214:215]
	global_load_dword v156, v[178:179], off
	v_lshl_add_u64 v[178:179], v[178:179], 0, v[214:215]
	global_load_dword v157, v[178:179], off
	v_lshl_add_u64 v[178:179], v[178:179], 0, v[214:215]
	global_load_dword v158, v[178:179], off
	v_lshl_add_u64 v[178:179], v[178:179], 0, v[214:215]
	global_load_dword v159, v[178:179], off
	v_lshl_add_u64 v[178:179], v[178:179], 0, v[214:215]
	global_load_dword v160, v[178:179], off
	v_lshl_add_u64 v[178:179], v[178:179], 0, v[214:215]
	global_load_dword v161, v[178:179], off
	v_lshl_add_u64 v[178:179], v[178:179], 0, v[214:215]
	global_load_dword v162, v[178:179], off
	v_lshl_add_u64 v[178:179], v[178:179], 0, v[214:215]
	global_load_dword v163, v[178:179], off
	v_lshl_add_u64 v[178:179], v[178:179], 0, v[214:215]
	global_load_dword v164, v[178:179], off
	v_lshl_add_u64 v[178:179], v[178:179], 0, v[214:215]
	global_load_dword v165, v[178:179], off
	v_lshl_add_u64 v[178:179], v[178:179], 0, v[214:215]
	global_load_dword v166, v[178:179], off
	v_lshl_add_u64 v[178:179], v[178:179], 0, v[214:215]
	global_load_dword v167, v[178:179], off
	v_lshl_add_u64 v[178:179], v[178:179], 0, v[214:215]
	global_load_dword v168, v[178:179], off
	v_lshl_add_u64 v[178:179], v[178:179], 0, v[214:215]
	global_load_dword v169, v[178:179], off
	v_lshl_add_u64 v[178:179], v[178:179], 0, v[214:215]
	global_load_dword v170, v[178:179], off
	v_lshl_add_u64 v[178:179], v[178:179], 0, v[214:215]
	global_load_dword v171, v[178:179], off
	v_lshl_add_u64 v[178:179], v[178:179], 0, v[214:215]
	global_load_dword v172, v[178:179], off
	v_lshl_add_u64 v[178:179], v[178:179], 0, v[214:215]
	global_load_dword v173, v[178:179], off
	v_lshl_add_u64 v[178:179], v[178:179], 0, v[214:215]
	global_load_dword v174, v[178:179], off
	v_lshl_add_u64 v[178:179], v[178:179], 0, v[214:215]
	global_load_dword v175, v[178:179], off
	v_lshl_add_u64 v[178:179], v[178:179], 0, v[214:215]
	global_load_dword v176, v[178:179], off
	v_lshl_add_u64 v[178:179], v[178:179], 0, v[214:215]
	global_load_dword v177, v[178:179], off
	v_lshl_add_u64 v[178:179], v[178:179], 0, v[214:215]
	global_load_dword v8, v[178:179], off
	v_lshl_add_u64 v[178:179], v[178:179], 0, v[214:215]
	global_load_dword v7, v[178:179], off
	v_lshl_add_u64 v[178:179], v[178:179], 0, v[214:215]
	global_load_dword v10, v[178:179], off
	v_lshl_add_u64 v[178:179], v[178:179], 0, v[214:215]
; #define LAS __attribute__((address_space(3)))
; #define LDS_WAIT() asm volatile("s_waitcnt lgkmcnt(0)" ::: "memory")
; __device__ __forceinline__ unsigned pk2(float lo, float hi) { pk2_f2_t v = {lo, hi}; pk2_b2_t b = __builtin_convertvector(v, pk2_b2_t); return __builtin_bit_cast(unsigned, b); }
; __device__ __forceinline__ void tr64_item(const float* W, int K, int N, int srccol, bf16* WT, int destrow0  , int k0, LAS unsigned char* scr, int lane) {
;     const float* src = W + (size_t)k0 * N + (srccol >= 0 ? srccol : 0);
; #pragma unroll
;     for (int h = 0; h < 2; ++h) { float v[32];
; #pragma unroll
;         for (int i = 0; i < 32; ++i) v[i] = srccol >= 0 ? src[(size_t)(32 * h + i) * N] : 0.f;
; #pragma unroll
;         for (int c = 0; c < 4; ++c) { v4u o; o.x = pk2(v[8 * c], v[8 * c + 1]); o.y = pk2(v[8 * c + 2], v[8 * c + 3]); o.z = pk2(v[8 * c + 4], v[8 * c + 5]); o.w = pk2(v[8 * c + 6], v[8 * c + 7]);
;             *(LAS v4u*)(scr + lane * 128 + (((4 * h + c) ^ (lane & 7)) << 4)) = o; } }
;     LDS_WAIT(); asm volatile("" ::: "memory");
;     const int r = lane >> 3, c = lane & 7;
; #pragma unroll
;     for (int j = 0; j < 8; ++j) { const int n = r + 8 * j; const v4u o = *(const LAS v4u*)(scr + n * 128 + ((c ^ (n & 7)) << 4));
;         *(v4u*)(WT + (size_t)(destrow0 + n) * K + k0 + 8 * c) = o; }
	global_load_dword v9, v[178:179], off
	v_lshl_add_u64 v[178:179], v[178:179], 0, v[214:215]
	global_load_dword v12, v[178:179], off
	v_lshl_add_u64 v[178:179], v[178:179], 0, v[214:215]
	global_load_dword v11, v[178:179], off
	v_lshl_add_u64 v[178:179], v[178:179], 0, v[214:215]
	global_load_dword v14, v[178:179], off
	v_lshl_add_u64 v[178:179], v[178:179], 0, v[214:215]
	global_load_dword v13, v[178:179], off
	v_lshl_add_u64 v[178:179], v[178:179], 0, v[214:215]
	global_load_dword v16, v[178:179], off
	v_lshl_add_u64 v[178:179], v[178:179], 0, v[214:215]
	global_load_dword v15, v[178:179], off
	v_lshl_add_u64 v[178:179], v[178:179], 0, v[214:215]
	global_load_dword v18, v[178:179], off
	v_lshl_add_u64 v[178:179], v[178:179], 0, v[214:215]
	global_load_dword v17, v[178:179], off
	v_lshl_add_u64 v[178:179], v[178:179], 0, v[214:215]
	global_load_dword v20, v[178:179], off
	v_lshl_add_u64 v[178:179], v[178:179], 0, v[214:215]
	global_load_dword v19, v[178:179], off
	v_lshl_add_u64 v[178:179], v[178:179], 0, v[214:215]
	global_load_dword v22, v[178:179], off
	v_lshl_add_u64 v[178:179], v[178:179], 0, v[214:215]
	global_load_dword v21, v[178:179], off
	v_lshl_add_u64 v[178:179], v[178:179], 0, v[214:215]
	global_load_dword v24, v[178:179], off
	v_lshl_add_u64 v[178:179], v[178:179], 0, v[214:215]
	global_load_dword v23, v[178:179], off
	v_lshl_add_u64 v[178:179], v[178:179], 0, v[214:215]
	global_load_dword v26, v[178:179], off
	v_lshl_add_u64 v[178:179], v[178:179], 0, v[214:215]
	global_load_dword v25, v[178:179], off
	v_lshl_add_u64 v[178:179], v[178:179], 0, v[214:215]
	global_load_dword v28, v[178:179], off
	v_lshl_add_u64 v[178:179], v[178:179], 0, v[214:215]
	global_load_dword v27, v[178:179], off
	v_lshl_add_u64 v[178:179], v[178:179], 0, v[214:215]
	global_load_dword v30, v[178:179], off
	v_lshl_add_u64 v[178:179], v[178:179], 0, v[214:215]
	global_load_dword v29, v[178:179], off
	v_lshl_add_u64 v[178:179], v[178:179], 0, v[214:215]
	global_load_dword v32, v[178:179], off
	v_lshl_add_u64 v[178:179], v[178:179], 0, v[214:215]
	global_load_dword v31, v[178:179], off
	v_lshl_add_u64 v[178:179], v[178:179], 0, v[214:215]
	global_load_dword v34, v[178:179], off
	v_lshl_add_u64 v[178:179], v[178:179], 0, v[214:215]
	global_load_dword v33, v[178:179], off
	v_lshl_add_u64 v[178:179], v[178:179], 0, v[214:215]
	global_load_dword v36, v[178:179], off
	v_lshl_add_u64 v[178:179], v[178:179], 0, v[214:215]
	global_load_dword v35, v[178:179], off
	v_lshl_add_u64 v[178:179], v[178:179], 0, v[214:215]
	global_load_dword v38, v[178:179], off
	v_lshl_add_u64 v[178:179], v[178:179], 0, v[214:215]
	global_load_dword v37, v[178:179], off
	s_or_b64 exec, exec, s[16:17]
	s_waitcnt vmcnt(32)
	v_lshlrev_b32_e32 v2, 4, v1
	v_lshl_add_u32 v6, v1, 7, s46
	v_and_b32_e32 v2, 0x70, v2
	v_cvt_pk_bf16_f32 v180, v146, v147
	v_cvt_pk_bf16_f32 v181, v148, v149
	v_cvt_pk_bf16_f32 v182, v150, v151
	v_cvt_pk_bf16_f32 v183, v152, v153
	v_add_u32_e32 v184, v6, v2
	ds_write_b128 v184, v[180:183]
	v_cvt_pk_bf16_f32 v180, v154, v155
	v_cvt_pk_bf16_f32 v181, v156, v157
	v_cvt_pk_bf16_f32 v182, v158, v159
	v_cvt_pk_bf16_f32 v183, v160, v161
	v_xad_u32 v184, v2, 16, v6
	ds_write_b128 v184, v[180:183]
	v_cvt_pk_bf16_f32 v180, v162, v163
	v_cvt_pk_bf16_f32 v181, v164, v165
	v_cvt_pk_bf16_f32 v182, v166, v167
	v_cvt_pk_bf16_f32 v183, v168, v169
	v_xad_u32 v184, v2, 32, v6
	ds_write_b128 v184, v[180:183]
	v_cvt_pk_bf16_f32 v180, v170, v171
	v_cvt_pk_bf16_f32 v181, v172, v173
	v_cvt_pk_bf16_f32 v182, v174, v175
	v_cvt_pk_bf16_f32 v183, v176, v177
	v_xad_u32 v184, v2, 48, v6
	ds_write_b128 v184, v[180:183]
	s_waitcnt vmcnt(0)
	s_waitcnt vmcnt(0) lgkmcnt(0)
	v_cvt_pk_bf16_f32 v8, v8, v7
	v_cvt_pk_bf16_f32 v9, v10, v9
	v_cvt_pk_bf16_f32 v10, v12, v11
	v_cvt_pk_bf16_f32 v11, v14, v13
	v_xad_u32 v4, v2, 64, v6
	ds_write_b128 v4, v[8:11]
	v_cvt_pk_bf16_f32 v8, v16, v15
	v_cvt_pk_bf16_f32 v9, v18, v17
	v_cvt_pk_bf16_f32 v10, v20, v19
	v_cvt_pk_bf16_f32 v11, v22, v21
	v_xad_u32 v4, v2, s92, v6
	ds_write_b128 v4, v[8:11]
	v_cvt_pk_bf16_f32 v8, v24, v23
	v_cvt_pk_bf16_f32 v9, v26, v25
	v_cvt_pk_bf16_f32 v10, v28, v27
	v_cvt_pk_bf16_f32 v11, v30, v29
	v_xad_u32 v4, v2, s81, v6
	ds_write_b128 v4, v[8:11]
	v_cvt_pk_bf16_f32 v8, v32, v31
	v_cvt_pk_bf16_f32 v9, v34, v33
	v_cvt_pk_bf16_f32 v10, v36, v35
	v_cvt_pk_bf16_f32 v11, v38, v37
	v_xad_u32 v4, v2, s85, v6
	v_ashrrev_i32_e32 v12, 3, v1
	s_lshl_b32 s7, s7, 6
	ds_write_b128 v4, v[8:11]
	v_xor_b32_e32 v4, v12, v1
	v_lshlrev_b32_e32 v4, 4, v4
	s_lshl_b32 s7, s7, 1
	v_and_b32_e32 v4, 0x70, v4
	s_add_u32 s8, s48, s7
	s_waitcnt lgkmcnt(0)
	v_add_u32_e32 v13, s46, v4
	s_addc_u32 s9, s49, 0
	v_lshl_add_u64 v[8:9], s[8:9], 0, v[2:3]
	v_lshl_add_u32 v2, v12, 7, v13
	ds_read_b128 v[4:7], v2
	v_add_u32_e32 v10, s4, v12
	v_ashrrev_i32_e32 v11, 31, v10
	v_lshlrev_b64 v[10:11], 12, v[10:11]
	v_lshl_add_u64 v[10:11], v[8:9], 0, v[10:11]
	v_add_u32_e32 v2, 8, v12
	s_waitcnt lgkmcnt(0)
	flat_store_dwordx4 v[10:11], v[4:7]
	v_add_u32_e32 v10, s4, v2
	v_ashrrev_i32_e32 v11, 31, v10
	v_lshl_add_u32 v4, v2, 7, v13
	ds_read_b128 v[4:7], v4
	v_lshlrev_b64 v[10:11], 12, v[10:11]
	v_lshl_add_u64 v[10:11], v[8:9], 0, v[10:11]
	v_add_u32_e32 v2, 16, v12
	s_mov_b64 s[24:25], 0
	s_waitcnt lgkmcnt(0)
	flat_store_dwordx4 v[10:11], v[4:7]
	v_add_u32_e32 v10, s4, v2
	v_ashrrev_i32_e32 v11, 31, v10
	v_lshl_add_u32 v4, v2, 7, v13
	ds_read_b128 v[4:7], v4
	v_lshlrev_b64 v[10:11], 12, v[10:11]
	v_lshl_add_u64 v[10:11], v[8:9], 0, v[10:11]
	v_add_u32_e32 v2, 24, v12
	s_waitcnt lgkmcnt(0)
	flat_store_dwordx4 v[10:11], v[4:7]
	v_add_u32_e32 v10, s4, v2
	s_nop 0
	v_lshl_add_u32 v4, v2, 7, v13
	ds_read_b128 v[4:7], v4
	v_ashrrev_i32_e32 v11, 31, v10
	v_lshlrev_b64 v[10:11], 12, v[10:11]
	v_lshl_add_u64 v[10:11], v[8:9], 0, v[10:11]
	v_add_u32_e32 v2, 32, v12
	s_waitcnt lgkmcnt(0)
	flat_store_dwordx4 v[10:11], v[4:7]
	v_add_u32_e32 v10, s4, v2
	v_ashrrev_i32_e32 v11, 31, v10
	v_lshl_add_u32 v4, v2, 7, v13
	ds_read_b128 v[4:7], v4
	v_lshlrev_b64 v[10:11], 12, v[10:11]
	v_lshl_add_u64 v[10:11], v[8:9], 0, v[10:11]
	v_add_u32_e32 v2, 40, v12
	s_waitcnt lgkmcnt(0)
	flat_store_dwordx4 v[10:11], v[4:7]
	v_add_u32_e32 v10, s4, v2
	s_nop 0
	v_lshl_add_u32 v4, v2, 7, v13
	ds_read_b128 v[4:7], v4
	v_ashrrev_i32_e32 v11, 31, v10
	v_lshlrev_b64 v[10:11], 12, v[10:11]
	v_lshl_add_u64 v[10:11], v[8:9], 0, v[10:11]
	v_add_u32_e32 v2, 48, v12
	s_waitcnt lgkmcnt(0)
	flat_store_dwordx4 v[10:11], v[4:7]
	v_add_u32_e32 v10, s4, v2
	v_ashrrev_i32_e32 v11, 31, v10
	v_lshl_add_u32 v4, v2, 7, v13
	ds_read_b128 v[4:7], v4
	v_lshlrev_b64 v[10:11], 12, v[10:11]
	v_lshl_add_u64 v[10:11], v[8:9], 0, v[10:11]
	v_add_u32_e32 v2, 56, v12
	s_waitcnt lgkmcnt(0)
	flat_store_dwordx4 v[10:11], v[4:7]
	v_add_u32_e32 v10, s4, v2
	s_nop 0
	v_lshl_add_u32 v4, v2, 7, v13
	ds_read_b128 v[4:7], v4
	v_ashrrev_i32_e32 v11, 31, v10
	v_lshlrev_b64 v[10:11], 12, v[10:11]
	v_lshl_add_u64 v[8:9], v[8:9], 0, v[10:11]
	s_waitcnt lgkmcnt(0)
	flat_store_dwordx4 v[8:9], v[4:7]
	s_waitcnt lgkmcnt(0)

; #define LAS __attribute__((address_space(3)))
; __device__ __forceinline__ unsigned pk2(float lo, float hi) { pk2_f2_t v = {lo, hi}; pk2_b2_t b = __builtin_convertvector(v, pk2_b2_t); return __builtin_bit_cast(unsigned, b); }
; __device__ __forceinline__ void tr64_item(const float* W, int K, int N, int srccol, bf16* WT, int destrow0  , int k0, LAS unsigned char* scr, int lane) {
;     const float* src = W + (size_t)k0 * N + (srccol >= 0 ? srccol : 0);
; #pragma unroll
;     for (int h = 0; h < 2; ++h) { float v[32];
; #pragma unroll
;         for (int i = 0; i < 32; ++i) v[i] = srccol >= 0 ? src[(size_t)(32 * h + i) * N] : 0.f;
; #pragma unroll
;         for (int c = 0; c < 4; ++c) { v4u o; o.x = pk2(v[8 * c], v[8 * c + 1]); o.y = pk2(v[8 * c + 2], v[8 * c + 3]); o.z = pk2(v[8 * c + 4], v[8 * c + 5]); o.w = pk2(v[8 * c + 6], v[8 * c + 7]);
;             *(LAS v4u*)(scr + lane * 128 + (((4 * h + c) ^ (lane & 7)) << 4)) = o; } }
; __device__ __forceinline__ void conv_item(const float* w_in, const float* w_out, const float* w_gate, const float* w_up, const float* w_down, unsigned char* ws, int layer, int r, LAS unsigned char* scr, int lane) {
;     ...
;         if (r < I_OUT) { const int nblk = DM / 64, kb = r / nblk, nb = r % nblk;
;             tr64_item(w_out + (size_t)layer * DM * DM, DM, DM, nb * 64 + lane, (bf16*)(wl + W_OUT), nb * 64, kb * 64, scr, lane); return; }
.LBB0_1719:
	s_and_b32 s7, s53, 0x1fc0
	s_and_b32 s4, s52, 0x7c0
	s_add_i32 s18, s7, 0xffffe800
	v_add_u32_e32 v2, s4, v1
	s_lshl_b64 s[8:9], s[18:19], 13
	s_waitcnt lgkmcnt(0)
	s_add_u32 s8, s14, s8
	v_cmp_lt_i32_e64 s[40:41], -1, v2
	s_addc_u32 s9, s15, s9
	v_mov_b32_e32 v7, 0
	v_cndmask_b32_e64 v2, 0, v2, s[40:41]
	v_lshl_add_u64 v[4:5], v[2:3], 2, s[8:9]
	v_mov_b32_e32 v2, 0
	s_cmp_eq_u64 s[40:41], exec
	s_cbranch_scc1 .Lmy_cv6_nz
	v_mov_b32_e32 v146, 0
	v_mov_b32_e32 v147, 0
	v_mov_b32_e32 v148, 0
	v_mov_b32_e32 v149, 0
	v_mov_b32_e32 v150, 0
	v_mov_b32_e32 v151, 0
	v_mov_b32_e32 v152, 0
	v_mov_b32_e32 v153, 0
	v_mov_b32_e32 v154, 0
	v_mov_b32_e32 v155, 0
	v_mov_b32_e32 v156, 0
	v_mov_b32_e32 v157, 0
	v_mov_b32_e32 v158, 0
	v_mov_b32_e32 v159, 0
	v_mov_b32_e32 v160, 0
	v_mov_b32_e32 v161, 0
	v_mov_b32_e32 v162, 0
	v_mov_b32_e32 v163, 0
	v_mov_b32_e32 v164, 0
	v_mov_b32_e32 v165, 0
	v_mov_b32_e32 v166, 0
	v_mov_b32_e32 v167, 0
	v_mov_b32_e32 v168, 0
	v_mov_b32_e32 v169, 0
	v_mov_b32_e32 v170, 0
	v_mov_b32_e32 v171, 0
	v_mov_b32_e32 v172, 0
	v_mov_b32_e32 v173, 0
	v_mov_b32_e32 v174, 0
	v_mov_b32_e32 v175, 0
	v_mov_b32_e32 v176, 0
	v_mov_b32_e32 v177, 0
	v_mov_b32_e32 v8, 0
	v_mov_b32_e32 v7, 0
	v_mov_b32_e32 v10, 0
	v_mov_b32_e32 v9, 0
	v_mov_b32_e32 v12, 0
	v_mov_b32_e32 v11, 0
	v_mov_b32_e32 v14, 0
	v_mov_b32_e32 v13, 0
	v_mov_b32_e32 v16, 0
	v_mov_b32_e32 v15, 0
	v_mov_b32_e32 v18, 0
	v_mov_b32_e32 v17, 0
	v_mov_b32_e32 v20, 0
	v_mov_b32_e32 v19, 0
	v_mov_b32_e32 v22, 0
	v_mov_b32_e32 v21, 0
	v_mov_b32_e32 v24, 0
	v_mov_b32_e32 v23, 0
	v_mov_b32_e32 v26, 0
	v_mov_b32_e32 v25, 0
	v_mov_b32_e32 v28, 0
	v_mov_b32_e32 v27, 0
	v_mov_b32_e32 v30, 0
	v_mov_b32_e32 v29, 0
	v_mov_b32_e32 v32, 0
	v_mov_b32_e32 v31, 0
	v_mov_b32_e32 v34, 0
	v_mov_b32_e32 v33, 0
	v_mov_b32_e32 v36, 0
	v_mov_b32_e32 v35, 0
	v_mov_b32_e32 v38, 0
	v_mov_b32_e32 v37, 0
.Lmy_cv6_nz:
	v_mov_b64_e32 v[178:179], v[4:5]
	v_mov_b32_e32 v214, 0x2000
	v_mov_b32_e32 v215, 0
	s_and_saveexec_b64 s[14:15], s[40:41]
	global_load_dword v146, v[178:179], off
	v_lshl_add_u64 v[178:179], v[178:179], 0, v[214:215]
	global_load_dword v147, v[178:179], off
	v_lshl_add_u64 v[178:179], v[178:179], 0, v[214:215]
	global_load_dword v148, v[178:179], off
	v_lshl_add_u64 v[178:179], v[178:179], 0, v[214:215]
	global_load_dword v149, v[178:179], off
	v_lshl_add_u64 v[178:179], v[178:179], 0, v[214:215]
	global_load_dword v150, v[178:179], off
	v_lshl_add_u64 v[178:179], v[178:179], 0, v[214:215]
	global_load_dword v151, v[178:179], off
	v_lshl_add_u64 v[178:179], v[178:179], 0, v[214:215]
	global_load_dword v152, v[178:179], off
	v_lshl_add_u64 v[178:179], v[178:179], 0, v[214:215]
	global_load_dword v153, v[178:179], off
	v_lshl_add_u64 v[178:179], v[178:179], 0, v[214:215]
	global_load_dword v154, v[178:179], off
	v_lshl_add_u64 v[178:179], v[178:179], 0, v[214:215]
	global_load_dword v155, v[178:179], off
	v_lshl_add_u64 v[178:179], v[178:179], 0, v[214:215]
	global_load_dword v156, v[178:179], off
	v_lshl_add_u64 v[178:179], v[178:179], 0, v[214:215]
	global_load_dword v157, v[178:179], off
	v_lshl_add_u64 v[178:179], v[178:179], 0, v[214:215]
	global_load_dword v158, v[178:179], off
	v_lshl_add_u64 v[178:179], v[178:179], 0, v[214:215]
	global_load_dword v159, v[178:179], off
	v_lshl_add_u64 v[178:179], v[178:179], 0, v[214:215]
	global_load_dword v160, v[178:179], off
	v_lshl_add_u64 v[178:179], v[178:179], 0, v[214:215]
	global_load_dword v161, v[178:179], off
	v_lshl_add_u64 v[178:179], v[178:179], 0, v[214:215]
	global_load_dword v162, v[178:179], off
	v_lshl_add_u64 v[178:179], v[178:179], 0, v[214:215]
	global_load_dword v163, v[178:179], off
	v_lshl_add_u64 v[178:179], v[178:179], 0, v[214:215]
	global_load_dword v164, v[178:179], off
	v_lshl_add_u64 v[178:179], v[178:179], 0, v[214:215]
	global_load_dword v165, v[178:179], off
	v_lshl_add_u64 v[178:179], v[178:179], 0, v[214:215]
	global_load_dword v166, v[178:179], off
	v_lshl_add_u64 v[178:179], v[178:179], 0, v[214:215]
	global_load_dword v167, v[178:179], off
	v_lshl_add_u64 v[178:179], v[178:179], 0, v[214:215]
	global_load_dword v168, v[178:179], off
	v_lshl_add_u64 v[178:179], v[178:179], 0, v[214:215]
	global_load_dword v169, v[178:179], off
	v_lshl_add_u64 v[178:179], v[178:179], 0, v[214:215]
	global_load_dword v170, v[178:179], off
	v_lshl_add_u64 v[178:179], v[178:179], 0, v[214:215]
	global_load_dword v171, v[178:179], off
	v_lshl_add_u64 v[178:179], v[178:179], 0, v[214:215]
	global_load_dword v172, v[178:179], off
	v_lshl_add_u64 v[178:179], v[178:179], 0, v[214:215]
	global_load_dword v173, v[178:179], off
	v_lshl_add_u64 v[178:179], v[178:179], 0, v[214:215]
	global_load_dword v174, v[178:179], off
	v_lshl_add_u64 v[178:179], v[178:179], 0, v[214:215]
	global_load_dword v175, v[178:179], off
	v_lshl_add_u64 v[178:179], v[178:179], 0, v[214:215]
	global_load_dword v176, v[178:179], off
	v_lshl_add_u64 v[178:179], v[178:179], 0, v[214:215]
	global_load_dword v177, v[178:179], off
	v_lshl_add_u64 v[178:179], v[178:179], 0, v[214:215]
	global_load_dword v8, v[178:179], off
	v_lshl_add_u64 v[178:179], v[178:179], 0, v[214:215]
	global_load_dword v7, v[178:179], off
	v_lshl_add_u64 v[178:179], v[178:179], 0, v[214:215]
	global_load_dword v10, v[178:179], off
	v_lshl_add_u64 v[178:179], v[178:179], 0, v[214:215]
	global_load_dword v9, v[178:179], off
	v_lshl_add_u64 v[178:179], v[178:179], 0, v[214:215]
	global_load_dword v12, v[178:179], off
	v_lshl_add_u64 v[178:179], v[178:179], 0, v[214:215]
	global_load_dword v11, v[178:179], off
	v_lshl_add_u64 v[178:179], v[178:179], 0, v[214:215]
	global_load_dword v14, v[178:179], off
; #define LAS __attribute__((address_space(3)))
; #define LDS_WAIT() asm volatile("s_waitcnt lgkmcnt(0)" ::: "memory")
; __device__ __forceinline__ unsigned pk2(float lo, float hi) { pk2_f2_t v = {lo, hi}; pk2_b2_t b = __builtin_convertvector(v, pk2_b2_t); return __builtin_bit_cast(unsigned, b); }
; __device__ __forceinline__ void tr64_item(const float* W, int K, int N, int srccol, bf16* WT, int destrow0  , int k0, LAS unsigned char* scr, int lane) {
;     const float* src = W + (size_t)k0 * N + (srccol >= 0 ? srccol : 0);
; #pragma unroll
;     for (int h = 0; h < 2; ++h) { float v[32];
; #pragma unroll
;         for (int i = 0; i < 32; ++i) v[i] = srccol >= 0 ? src[(size_t)(32 * h + i) * N] : 0.f;
; #pragma unroll
;         for (int c = 0; c < 4; ++c) { v4u o; o.x = pk2(v[8 * c], v[8 * c + 1]); o.y = pk2(v[8 * c + 2], v[8 * c + 3]); o.z = pk2(v[8 * c + 4], v[8 * c + 5]); o.w = pk2(v[8 * c + 6], v[8 * c + 7]);
;             *(LAS v4u*)(scr + lane * 128 + (((4 * h + c) ^ (lane & 7)) << 4)) = o; } }
;     LDS_WAIT(); asm volatile("" ::: "memory");
;     const int r = lane >> 3, c = lane & 7;
; #pragma unroll
;     for (int j = 0; j < 8; ++j) { const int n = r + 8 * j; const v4u o = *(const LAS v4u*)(scr + n * 128 + ((c ^ (n & 7)) << 4));
;         *(v4u*)(WT + (size_t)(destrow0 + n) * K + k0 + 8 * c) = o; }
	v_lshl_add_u64 v[178:179], v[178:179], 0, v[214:215]
	global_load_dword v13, v[178:179], off
	v_lshl_add_u64 v[178:179], v[178:179], 0, v[214:215]
	global_load_dword v16, v[178:179], off
	v_lshl_add_u64 v[178:179], v[178:179], 0, v[214:215]
	global_load_dword v15, v[178:179], off
	v_lshl_add_u64 v[178:179], v[178:179], 0, v[214:215]
	global_load_dword v18, v[178:179], off
	v_lshl_add_u64 v[178:179], v[178:179], 0, v[214:215]
	global_load_dword v17, v[178:179], off
	v_lshl_add_u64 v[178:179], v[178:179], 0, v[214:215]
	global_load_dword v20, v[178:179], off
	v_lshl_add_u64 v[178:179], v[178:179], 0, v[214:215]
	global_load_dword v19, v[178:179], off
	v_lshl_add_u64 v[178:179], v[178:179], 0, v[214:215]
	global_load_dword v22, v[178:179], off
	v_lshl_add_u64 v[178:179], v[178:179], 0, v[214:215]
	global_load_dword v21, v[178:179], off
	v_lshl_add_u64 v[178:179], v[178:179], 0, v[214:215]
	global_load_dword v24, v[178:179], off
	v_lshl_add_u64 v[178:179], v[178:179], 0, v[214:215]
	global_load_dword v23, v[178:179], off
	v_lshl_add_u64 v[178:179], v[178:179], 0, v[214:215]
	global_load_dword v26, v[178:179], off
	v_lshl_add_u64 v[178:179], v[178:179], 0, v[214:215]
	global_load_dword v25, v[178:179], off
	v_lshl_add_u64 v[178:179], v[178:179], 0, v[214:215]
	global_load_dword v28, v[178:179], off
	v_lshl_add_u64 v[178:179], v[178:179], 0, v[214:215]
	global_load_dword v27, v[178:179], off
	v_lshl_add_u64 v[178:179], v[178:179], 0, v[214:215]
	global_load_dword v30, v[178:179], off
	v_lshl_add_u64 v[178:179], v[178:179], 0, v[214:215]
	global_load_dword v29, v[178:179], off
	v_lshl_add_u64 v[178:179], v[178:179], 0, v[214:215]
	global_load_dword v32, v[178:179], off
	v_lshl_add_u64 v[178:179], v[178:179], 0, v[214:215]
	global_load_dword v31, v[178:179], off
	v_lshl_add_u64 v[178:179], v[178:179], 0, v[214:215]
	global_load_dword v34, v[178:179], off
	v_lshl_add_u64 v[178:179], v[178:179], 0, v[214:215]
	global_load_dword v33, v[178:179], off
	v_lshl_add_u64 v[178:179], v[178:179], 0, v[214:215]
	global_load_dword v36, v[178:179], off
	v_lshl_add_u64 v[178:179], v[178:179], 0, v[214:215]
	global_load_dword v35, v[178:179], off
	v_lshl_add_u64 v[178:179], v[178:179], 0, v[214:215]
	global_load_dword v38, v[178:179], off
	v_lshl_add_u64 v[178:179], v[178:179], 0, v[214:215]
	global_load_dword v37, v[178:179], off
	s_or_b64 exec, exec, s[14:15]
	s_waitcnt vmcnt(32)
	v_lshlrev_b32_e32 v2, 4, v1
	v_lshl_add_u32 v6, v1, 7, s46
	v_and_b32_e32 v2, 0x70, v2
	v_cvt_pk_bf16_f32 v180, v146, v147
	v_cvt_pk_bf16_f32 v181, v148, v149
	v_cvt_pk_bf16_f32 v182, v150, v151
	v_cvt_pk_bf16_f32 v183, v152, v153
	v_add_u32_e32 v184, v6, v2
	ds_write_b128 v184, v[180:183]
	v_cvt_pk_bf16_f32 v180, v154, v155
	v_cvt_pk_bf16_f32 v181, v156, v157
	v_cvt_pk_bf16_f32 v182, v158, v159
	v_cvt_pk_bf16_f32 v183, v160, v161
	v_xad_u32 v184, v2, 16, v6
	ds_write_b128 v184, v[180:183]
	v_cvt_pk_bf16_f32 v180, v162, v163
	v_cvt_pk_bf16_f32 v181, v164, v165
	v_cvt_pk_bf16_f32 v182, v166, v167
	v_cvt_pk_bf16_f32 v183, v168, v169
	v_xad_u32 v184, v2, 32, v6
	ds_write_b128 v184, v[180:183]
	v_cvt_pk_bf16_f32 v180, v170, v171
	v_cvt_pk_bf16_f32 v181, v172, v173
	v_cvt_pk_bf16_f32 v182, v174, v175
	v_cvt_pk_bf16_f32 v183, v176, v177
	v_xad_u32 v184, v2, 48, v6
	ds_write_b128 v184, v[180:183]
	s_waitcnt vmcnt(0)
	s_waitcnt vmcnt(0) lgkmcnt(0)
	v_cvt_pk_bf16_f32 v8, v8, v7
	v_cvt_pk_bf16_f32 v9, v10, v9
	v_cvt_pk_bf16_f32 v10, v12, v11
	v_cvt_pk_bf16_f32 v11, v14, v13
	v_xad_u32 v4, v2, 64, v6
	ds_write_b128 v4, v[8:11]
	v_cvt_pk_bf16_f32 v8, v16, v15
	v_cvt_pk_bf16_f32 v9, v18, v17
	v_cvt_pk_bf16_f32 v10, v20, v19
	v_cvt_pk_bf16_f32 v11, v22, v21
	v_xad_u32 v4, v2, s92, v6
	ds_write_b128 v4, v[8:11]
	v_cvt_pk_bf16_f32 v8, v24, v23
	v_cvt_pk_bf16_f32 v9, v26, v25
	v_cvt_pk_bf16_f32 v10, v28, v27
	v_cvt_pk_bf16_f32 v11, v30, v29
	v_xad_u32 v4, v2, s81, v6
	ds_write_b128 v4, v[8:11]
	v_cvt_pk_bf16_f32 v8, v32, v31
	v_cvt_pk_bf16_f32 v9, v34, v33
	v_cvt_pk_bf16_f32 v10, v36, v35
	v_cvt_pk_bf16_f32 v11, v38, v37
	v_xad_u32 v4, v2, s85, v6
	v_ashrrev_i32_e32 v12, 3, v1
	ds_write_b128 v4, v[8:11]
	v_xor_b32_e32 v4, v12, v1
	v_lshlrev_b32_e32 v4, 4, v4
	s_lshl_b64 s[8:9], s[18:19], 1
	v_and_b32_e32 v4, 0x70, v4
	s_add_u32 s8, s50, s8
	s_waitcnt lgkmcnt(0)
	v_add_u32_e32 v13, s46, v4
	s_addc_u32 s9, s51, s9
	v_lshl_add_u64 v[8:9], s[8:9], 0, v[2:3]
	v_lshl_add_u32 v2, v12, 7, v13
	ds_read_b128 v[4:7], v2
	v_add_u32_e32 v10, s4, v12
	v_ashrrev_i32_e32 v11, 31, v10
	v_lshlrev_b64 v[10:11], 12, v[10:11]
	v_lshl_add_u64 v[10:11], v[8:9], 0, v[10:11]
	v_add_u32_e32 v2, 8, v12
	s_waitcnt lgkmcnt(0)
	flat_store_dwordx4 v[10:11], v[4:7]
	v_add_u32_e32 v10, s4, v2
	v_ashrrev_i32_e32 v11, 31, v10
	v_lshl_add_u32 v4, v2, 7, v13
	ds_read_b128 v[4:7], v4
	v_lshlrev_b64 v[10:11], 12, v[10:11]
	v_lshl_add_u64 v[10:11], v[8:9], 0, v[10:11]
	v_add_u32_e32 v2, 16, v12
	s_waitcnt lgkmcnt(0)
	flat_store_dwordx4 v[10:11], v[4:7]
	v_add_u32_e32 v10, s4, v2
	s_nop 0
	v_lshl_add_u32 v4, v2, 7, v13
	ds_read_b128 v[4:7], v4
	v_ashrrev_i32_e32 v11, 31, v10
	v_lshlrev_b64 v[10:11], 12, v[10:11]
	v_lshl_add_u64 v[10:11], v[8:9], 0, v[10:11]
	v_add_u32_e32 v2, 24, v12
	s_waitcnt lgkmcnt(0)
	flat_store_dwordx4 v[10:11], v[4:7]
	v_add_u32_e32 v10, s4, v2
	v_ashrrev_i32_e32 v11, 31, v10
	v_lshl_add_u32 v4, v2, 7, v13
	ds_read_b128 v[4:7], v4
	v_lshlrev_b64 v[10:11], 12, v[10:11]
	v_lshl_add_u64 v[10:11], v[8:9], 0, v[10:11]
	v_add_u32_e32 v2, 32, v12
	s_waitcnt lgkmcnt(0)
	flat_store_dwordx4 v[10:11], v[4:7]
	v_add_u32_e32 v10, s4, v2
	s_nop 0
	v_lshl_add_u32 v4, v2, 7, v13
	ds_read_b128 v[4:7], v4
	v_ashrrev_i32_e32 v11, 31, v10
	v_lshlrev_b64 v[10:11], 12, v[10:11]
	v_lshl_add_u64 v[10:11], v[8:9], 0, v[10:11]
	v_add_u32_e32 v2, 40, v12
	s_waitcnt lgkmcnt(0)
	flat_store_dwordx4 v[10:11], v[4:7]
	v_add_u32_e32 v10, s4, v2
	v_ashrrev_i32_e32 v11, 31, v10
	v_lshl_add_u32 v4, v2, 7, v13
	ds_read_b128 v[4:7], v4
	v_lshlrev_b64 v[10:11], 12, v[10:11]
	v_lshl_add_u64 v[10:11], v[8:9], 0, v[10:11]
	v_add_u32_e32 v2, 48, v12
	s_waitcnt lgkmcnt(0)
	flat_store_dwordx4 v[10:11], v[4:7]
	v_add_u32_e32 v10, s4, v2
	s_nop 0
	v_lshl_add_u32 v4, v2, 7, v13
	ds_read_b128 v[4:7], v4
	v_ashrrev_i32_e32 v11, 31, v10
	v_lshlrev_b64 v[10:11], 12, v[10:11]
	v_lshl_add_u64 v[10:11], v[8:9], 0, v[10:11]
	v_add_u32_e32 v2, 56, v12
	s_waitcnt lgkmcnt(0)
	flat_store_dwordx4 v[10:11], v[4:7]
	v_add_u32_e32 v10, s4, v2
	v_ashrrev_i32_e32 v11, 31, v10
	v_lshl_add_u32 v4, v2, 7, v13
	ds_read_b128 v[4:7], v4
	v_lshlrev_b64 v[10:11], 12, v[10:11]
	v_lshl_add_u64 v[8:9], v[8:9], 0, v[10:11]
	s_waitcnt lgkmcnt(0)
	flat_store_dwordx4 v[8:9], v[4:7]
	s_waitcnt lgkmcnt(0)

; #define LAS __attribute__((address_space(3)))
; __device__ __forceinline__ unsigned pk2(float lo, float hi) { pk2_f2_t v = {lo, hi}; pk2_b2_t b = __builtin_convertvector(v, pk2_b2_t); return __builtin_bit_cast(unsigned, b); }
; __device__ __forceinline__ void tr64_item(const float* W, int K, int N, int srccol, bf16* WT, int destrow0  , int k0, LAS unsigned char* scr, int lane) {
;     const float* src = W + (size_t)k0 * N + (srccol >= 0 ? srccol : 0);
; #pragma unroll
;     for (int h = 0; h < 2; ++h) { float v[32];
; #pragma unroll
;         for (int i = 0; i < 32; ++i) v[i] = srccol >= 0 ? src[(size_t)(32 * h + i) * N] : 0.f;
; #pragma unroll
;         for (int c = 0; c < 4; ++c) { v4u o; o.x = pk2(v[8 * c], v[8 * c + 1]); o.y = pk2(v[8 * c + 2], v[8 * c + 3]); o.z = pk2(v[8 * c + 4], v[8 * c + 5]); o.w = pk2(v[8 * c + 6], v[8 * c + 7]);
;             *(LAS v4u*)(scr + lane * 128 + (((4 * h + c) ^ (lane & 7)) << 4)) = o; } }
; __device__ __forceinline__ void conv_item(const float* w_in, const float* w_out, const float* w_gate, const float* w_up, const float* w_down, unsigned char* ws, int layer, int r, LAS unsigned char* scr, int lane) {
;     ...
;         if (r < I_IN) { const int nblk = NINP / 64, kb = r / nblk, nb = r % nblk;
;             tr64_item(w_in + (size_t)layer * DM * NIN, DM, NIN, src_col_in(nb * 64 + lane), (bf16*)(wl + W_IN), nb * 64, kb * 64, scr, lane); return; }
.LBB0_1864:
	s_or_b64 exec, exec, s[14:15]
	s_lshl_b32 s14, s7, 6
	s_mul_i32 s7, s7, 0x171f00
	s_mul_hi_i32 s6, s14, 0x5c7c
	s_add_u32 s2, s2, s7
	v_cmp_lt_i32_e64 s[40:41], -1, v2
	s_addc_u32 s3, s3, s6
	v_mov_b32_e32 v7, 0
	v_cndmask_b32_e64 v2, 0, v2, s[40:41]
	v_lshl_add_u64 v[4:5], v[2:3], 2, s[2:3]
	v_mov_b32_e32 v2, 0
	s_cmp_eq_u64 s[40:41], exec
	s_cbranch_scc1 .Lmy_cv7_nz
	v_mov_b32_e32 v146, 0
	v_mov_b32_e32 v147, 0
	v_mov_b32_e32 v148, 0
	v_mov_b32_e32 v149, 0
	v_mov_b32_e32 v150, 0
	v_mov_b32_e32 v151, 0
	v_mov_b32_e32 v152, 0
	v_mov_b32_e32 v153, 0
	v_mov_b32_e32 v154, 0
	v_mov_b32_e32 v155, 0
	v_mov_b32_e32 v156, 0
	v_mov_b32_e32 v157, 0
	v_mov_b32_e32 v158, 0
	v_mov_b32_e32 v159, 0
	v_mov_b32_e32 v160, 0
	v_mov_b32_e32 v161, 0
	v_mov_b32_e32 v162, 0
	v_mov_b32_e32 v163, 0
	v_mov_b32_e32 v164, 0
	v_mov_b32_e32 v165, 0
	v_mov_b32_e32 v166, 0
	v_mov_b32_e32 v167, 0
	v_mov_b32_e32 v168, 0
	v_mov_b32_e32 v169, 0
	v_mov_b32_e32 v170, 0
	v_mov_b32_e32 v171, 0
	v_mov_b32_e32 v172, 0
	v_mov_b32_e32 v173, 0
	v_mov_b32_e32 v174, 0
	v_mov_b32_e32 v175, 0
	v_mov_b32_e32 v176, 0
	v_mov_b32_e32 v177, 0
	v_mov_b32_e32 v8, 0
	v_mov_b32_e32 v7, 0
	v_mov_b32_e32 v10, 0
	v_mov_b32_e32 v9, 0
	v_mov_b32_e32 v12, 0
	v_mov_b32_e32 v11, 0
	v_mov_b32_e32 v14, 0
	v_mov_b32_e32 v13, 0
	v_mov_b32_e32 v16, 0
	v_mov_b32_e32 v15, 0
	v_mov_b32_e32 v18, 0
	v_mov_b32_e32 v17, 0
	v_mov_b32_e32 v20, 0
	v_mov_b32_e32 v19, 0
	v_mov_b32_e32 v22, 0
	v_mov_b32_e32 v21, 0
	v_mov_b32_e32 v24, 0
	v_mov_b32_e32 v23, 0
	v_mov_b32_e32 v26, 0
	v_mov_b32_e32 v25, 0
	v_mov_b32_e32 v28, 0
	v_mov_b32_e32 v27, 0
	v_mov_b32_e32 v30, 0
	v_mov_b32_e32 v29, 0
	v_mov_b32_e32 v32, 0
	v_mov_b32_e32 v31, 0
	v_mov_b32_e32 v34, 0
	v_mov_b32_e32 v33, 0
	v_mov_b32_e32 v36, 0
	v_mov_b32_e32 v35, 0
	v_mov_b32_e32 v38, 0
	v_mov_b32_e32 v37, 0
.Lmy_cv7_nz:
	v_mov_b64_e32 v[178:179], v[4:5]
	v_mov_b32_e32 v214, 0x5c7c
	v_mov_b32_e32 v215, 0
	s_and_saveexec_b64 s[2:3], s[40:41]
	global_load_dword v146, v[178:179], off
	v_lshl_add_u64 v[178:179], v[178:179], 0, v[214:215]
	global_load_dword v147, v[178:179], off
	v_lshl_add_u64 v[178:179], v[178:179], 0, v[214:215]
	global_load_dword v148, v[178:179], off
	v_lshl_add_u64 v[178:179], v[178:179], 0, v[214:215]
	global_load_dword v149, v[178:179], off
	v_lshl_add_u64 v[178:179], v[178:179], 0, v[214:215]
	global_load_dword v150, v[178:179], off
	v_lshl_add_u64 v[178:179], v[178:179], 0, v[214:215]
	global_load_dword v151, v[178:179], off
	v_lshl_add_u64 v[178:179], v[178:179], 0, v[214:215]
	global_load_dword v152, v[178:179], off
	v_lshl_add_u64 v[178:179], v[178:179], 0, v[214:215]
	global_load_dword v153, v[178:179], off
	v_lshl_add_u64 v[178:179], v[178:179], 0, v[214:215]
	global_load_dword v154, v[178:179], off
	v_lshl_add_u64 v[178:179], v[178:179], 0, v[214:215]
	global_load_dword v155, v[178:179], off
	v_lshl_add_u64 v[178:179], v[178:179], 0, v[214:215]
	global_load_dword v156, v[178:179], off
	v_lshl_add_u64 v[178:179], v[178:179], 0, v[214:215]
	global_load_dword v157, v[178:179], off
	v_lshl_add_u64 v[178:179], v[178:179], 0, v[214:215]
	global_load_dword v158, v[178:179], off
	v_lshl_add_u64 v[178:179], v[178:179], 0, v[214:215]
	global_load_dword v159, v[178:179], off
	v_lshl_add_u64 v[178:179], v[178:179], 0, v[214:215]
	global_load_dword v160, v[178:179], off
	v_lshl_add_u64 v[178:179], v[178:179], 0, v[214:215]
	global_load_dword v161, v[178:179], off
	v_lshl_add_u64 v[178:179], v[178:179], 0, v[214:215]
	global_load_dword v162, v[178:179], off
	v_lshl_add_u64 v[178:179], v[178:179], 0, v[214:215]
	global_load_dword v163, v[178:179], off
	v_lshl_add_u64 v[178:179], v[178:179], 0, v[214:215]
	global_load_dword v164, v[178:179], off
	v_lshl_add_u64 v[178:179], v[178:179], 0, v[214:215]
	global_load_dword v165, v[178:179], off
	v_lshl_add_u64 v[178:179], v[178:179], 0, v[214:215]
	global_load_dword v166, v[178:179], off
	v_lshl_add_u64 v[178:179], v[178:179], 0, v[214:215]
	global_load_dword v167, v[178:179], off
	v_lshl_add_u64 v[178:179], v[178:179], 0, v[214:215]
	global_load_dword v168, v[178:179], off
	v_lshl_add_u64 v[178:179], v[178:179], 0, v[214:215]
	global_load_dword v169, v[178:179], off
	v_lshl_add_u64 v[178:179], v[178:179], 0, v[214:215]
	global_load_dword v170, v[178:179], off
	v_lshl_add_u64 v[178:179], v[178:179], 0, v[214:215]
	global_load_dword v171, v[178:179], off
	v_lshl_add_u64 v[178:179], v[178:179], 0, v[214:215]
	global_load_dword v172, v[178:179], off
; #define LAS __attribute__((address_space(3)))
; __device__ __forceinline__ unsigned pk2(float lo, float hi) { pk2_f2_t v = {lo, hi}; pk2_b2_t b = __builtin_convertvector(v, pk2_b2_t); return __builtin_bit_cast(unsigned, b); }
; __device__ __forceinline__ void tr64_item(const float* W, int K, int N, int srccol, bf16* WT, int destrow0  , int k0, LAS unsigned char* scr, int lane) {
;     const float* src = W + (size_t)k0 * N + (srccol >= 0 ? srccol : 0);
; #pragma unroll
;     for (int h = 0; h < 2; ++h) { float v[32];
; #pragma unroll
;         for (int i = 0; i < 32; ++i) v[i] = srccol >= 0 ? src[(size_t)(32 * h + i) * N] : 0.f;
; #pragma unroll
;         for (int c = 0; c < 4; ++c) { v4u o; o.x = pk2(v[8 * c], v[8 * c + 1]); o.y = pk2(v[8 * c + 2], v[8 * c + 3]); o.z = pk2(v[8 * c + 4], v[8 * c + 5]); o.w = pk2(v[8 * c + 6], v[8 * c + 7]);
;             *(LAS v4u*)(scr + lane * 128 + (((4 * h + c) ^ (lane & 7)) << 4)) = o; } }
	v_lshl_add_u64 v[178:179], v[178:179], 0, v[214:215]
	global_load_dword v173, v[178:179], off
	v_lshl_add_u64 v[178:179], v[178:179], 0, v[214:215]
	global_load_dword v174, v[178:179], off
	v_lshl_add_u64 v[178:179], v[178:179], 0, v[214:215]
	global_load_dword v175, v[178:179], off
	v_lshl_add_u64 v[178:179], v[178:179], 0, v[214:215]
	global_load_dword v176, v[178:179], off
	v_lshl_add_u64 v[178:179], v[178:179], 0, v[214:215]
	global_load_dword v177, v[178:179], off
	v_lshl_add_u64 v[178:179], v[178:179], 0, v[214:215]
	global_load_dword v8, v[178:179], off
	v_lshl_add_u64 v[178:179], v[178:179], 0, v[214:215]
	global_load_dword v7, v[178:179], off
	v_lshl_add_u64 v[178:179], v[178:179], 0, v[214:215]
	global_load_dword v10, v[178:179], off
	v_lshl_add_u64 v[178:179], v[178:179], 0, v[214:215]
	global_load_dword v9, v[178:179], off
	v_lshl_add_u64 v[178:179], v[178:179], 0, v[214:215]
	global_load_dword v12, v[178:179], off
	v_lshl_add_u64 v[178:179], v[178:179], 0, v[214:215]
	global_load_dword v11, v[178:179], off
	v_lshl_add_u64 v[178:179], v[178:179], 0, v[214:215]
	global_load_dword v14, v[178:179], off
	v_lshl_add_u64 v[178:179], v[178:179], 0, v[214:215]
	global_load_dword v13, v[178:179], off
	v_lshl_add_u64 v[178:179], v[178:179], 0, v[214:215]
	global_load_dword v16, v[178:179], off
	v_lshl_add_u64 v[178:179], v[178:179], 0, v[214:215]
	global_load_dword v15, v[178:179], off
	v_lshl_add_u64 v[178:179], v[178:179], 0, v[214:215]
	global_load_dword v18, v[178:179], off
	v_lshl_add_u64 v[178:179], v[178:179], 0, v[214:215]
	global_load_dword v17, v[178:179], off
	v_lshl_add_u64 v[178:179], v[178:179], 0, v[214:215]
	global_load_dword v20, v[178:179], off
	v_lshl_add_u64 v[178:179], v[178:179], 0, v[214:215]
	global_load_dword v19, v[178:179], off
	v_lshl_add_u64 v[178:179], v[178:179], 0, v[214:215]
	global_load_dword v22, v[178:179], off
	v_lshl_add_u64 v[178:179], v[178:179], 0, v[214:215]
	global_load_dword v21, v[178:179], off
	v_lshl_add_u64 v[178:179], v[178:179], 0, v[214:215]
	global_load_dword v24, v[178:179], off
	v_lshl_add_u64 v[178:179], v[178:179], 0, v[214:215]
	global_load_dword v23, v[178:179], off
	v_lshl_add_u64 v[178:179], v[178:179], 0, v[214:215]
	global_load_dword v26, v[178:179], off
	v_lshl_add_u64 v[178:179], v[178:179], 0, v[214:215]
	global_load_dword v25, v[178:179], off
	v_lshl_add_u64 v[178:179], v[178:179], 0, v[214:215]
	global_load_dword v28, v[178:179], off
	v_lshl_add_u64 v[178:179], v[178:179], 0, v[214:215]
	global_load_dword v27, v[178:179], off
	v_lshl_add_u64 v[178:179], v[178:179], 0, v[214:215]
	global_load_dword v30, v[178:179], off
	v_lshl_add_u64 v[178:179], v[178:179], 0, v[214:215]
	global_load_dword v29, v[178:179], off
	v_lshl_add_u64 v[178:179], v[178:179], 0, v[214:215]
	global_load_dword v32, v[178:179], off
	v_lshl_add_u64 v[178:179], v[178:179], 0, v[214:215]
	global_load_dword v31, v[178:179], off
	v_lshl_add_u64 v[178:179], v[178:179], 0, v[214:215]
	global_load_dword v34, v[178:179], off
	v_lshl_add_u64 v[178:179], v[178:179], 0, v[214:215]
	global_load_dword v33, v[178:179], off
	v_lshl_add_u64 v[178:179], v[178:179], 0, v[214:215]
	global_load_dword v36, v[178:179], off
	v_lshl_add_u64 v[178:179], v[178:179], 0, v[214:215]
	global_load_dword v35, v[178:179], off
	v_lshl_add_u64 v[178:179], v[178:179], 0, v[214:215]
	global_load_dword v38, v[178:179], off
	v_lshl_add_u64 v[178:179], v[178:179], 0, v[214:215]
	global_load_dword v37, v[178:179], off
	s_or_b64 exec, exec, s[2:3]
	s_waitcnt vmcnt(32)
	v_lshlrev_b32_e32 v2, 4, v1
	v_lshl_add_u32 v6, v1, 7, s46
	v_and_b32_e32 v2, 0x70, v2
	v_cvt_pk_bf16_f32 v180, v146, v147
	v_cvt_pk_bf16_f32 v181, v148, v149
	v_cvt_pk_bf16_f32 v182, v150, v151
	v_cvt_pk_bf16_f32 v183, v152, v153
	v_add_u32_e32 v184, v6, v2
	ds_write_b128 v184, v[180:183]
	v_cvt_pk_bf16_f32 v180, v154, v155
	v_cvt_pk_bf16_f32 v181, v156, v157
	v_cvt_pk_bf16_f32 v182, v158, v159
	v_cvt_pk_bf16_f32 v183, v160, v161
	v_xad_u32 v184, v2, 16, v6
	ds_write_b128 v184, v[180:183]
	v_cvt_pk_bf16_f32 v180, v162, v163
	v_cvt_pk_bf16_f32 v181, v164, v165
	v_cvt_pk_bf16_f32 v182, v166, v167
	v_cvt_pk_bf16_f32 v183, v168, v169
	v_xad_u32 v184, v2, 32, v6
	ds_write_b128 v184, v[180:183]
	v_cvt_pk_bf16_f32 v180, v170, v171
	v_cvt_pk_bf16_f32 v181, v172, v173
	v_cvt_pk_bf16_f32 v182, v174, v175
	v_cvt_pk_bf16_f32 v183, v176, v177
	v_xad_u32 v184, v2, 48, v6
	ds_write_b128 v184, v[180:183]
	s_waitcnt vmcnt(0)
	s_branch .LBB0_1454
